# v112 + FFT signal row kept in registers + pointer-table loads as plain (L2-served) loads
# baseline (speedup 1.0000x reference)
.LBB0_100:
	flat_load_dwordx2 v[0:1], v[68:69] offset:48
	flat_load_dwordx2 v[2:3], v[68:69] offset:88
	flat_load_dwordx2 v[4:5], v[68:69]
	flat_load_dwordx2 v[6:7], v[68:69] offset:16
	s_waitcnt vmcnt(0)
	s_and_b64 vcc, exec, s[6:7]
	s_waitcnt lgkmcnt(0)
	v_readfirstlane_b32 s5, v1
	v_readfirstlane_b32 s4, v0
	v_readfirstlane_b32 s1, v3
	v_readfirstlane_b32 s0, v2
	v_readfirstlane_b32 s63, v5
	v_readfirstlane_b32 s62, v4
	v_readfirstlane_b32 s65, v7
	v_readfirstlane_b32 s64, v6
	s_cbranch_vccnz .LBB0_99
	v_add_u32_e32 v44, s8, v87
	v_ashrrev_i32_e32 v45, 31, v44
	v_lshlrev_b64 v[70:71], 2, v[44:45]
	v_lshl_add_u64 v[36:37], s[0:1], 0, v[70:71]
	s_movk_i32 s0, 0x2000
	v_add_co_u32_e32 v24, vcc, s0, v36
	s_movk_i32 s0, 0x4000
	s_nop 0
	v_addc_co_u32_e32 v25, vcc, 0, v37, vcc
	v_add_co_u32_e32 v28, vcc, s0, v36
	s_movk_i32 s0, 0x6000
	s_nop 0
	v_addc_co_u32_e32 v29, vcc, 0, v37, vcc
	v_add_co_u32_e32 v32, vcc, s0, v36
	s_mov_b32 s0, 0x8000
	s_nop 0
	v_addc_co_u32_e32 v33, vcc, 0, v37, vcc
	v_add_co_u32_e32 v38, vcc, s0, v36
	s_mov_b32 s0, 0xa000
	s_nop 0
	v_addc_co_u32_e32 v39, vcc, 0, v37, vcc
	v_add_co_u32_e32 v40, vcc, s0, v36
	v_lshl_add_u64 v[0:1], s[4:5], 0, v[70:71]
	v_lshl_add_u64 v[4:5], s[40:41], 0, v[70:71]
	v_lshl_add_u64 v[8:9], s[26:27], 0, v[70:71]
	v_lshl_add_u64 v[12:13], s[44:45], 0, v[70:71]
	v_lshl_add_u64 v[16:17], s[42:43], 0, v[70:71]
	v_addc_co_u32_e32 v41, vcc, 0, v37, vcc
	flat_load_dwordx4 v[0:3], v[0:1]
	s_nop 0
	global_load_dwordx4 v[4:7], v[4:5], off
	s_nop 0
	global_load_dwordx4 v[8:11], v[8:9], off
	s_nop 0
	global_load_dwordx4 v[12:15], v[12:13], off
	s_nop 0
	global_load_dwordx4 v[16:19], v[16:17], off
	s_nop 0
	flat_load_dwordx4 v[20:23], v[36:37]
	s_nop 0
	flat_load_dwordx4 v[24:27], v[24:25]
	s_nop 0
	flat_load_dwordx4 v[28:31], v[28:29]
	s_nop 0
	flat_load_dwordx4 v[32:35], v[32:33]
	s_nop 0
	flat_load_dwordx4 v[36:39], v[38:39]
	s_nop 0
	flat_load_dwordx4 v[40:43], v[40:41]
	v_ashrrev_i32_e32 v91, 9, v44
	s_movk_i32 s0, 0x1ff
	v_cmp_gt_i32_e64 s[8:9], 2, v91
	v_cmp_lt_u32_e64 s[10:11], s0, v44
	v_lshlrev_b64 v[44:45], 1, v[44:45]
	v_cndmask_b32_e64 v95, 1, -1, s[8:9]
	v_lshl_add_u64 v[72:73], s[38:39], 0, v[44:45]
	v_lshl_add_u64 v[74:75], s[48:49], 0, v[44:45]
	v_lshl_add_u64 v[76:77], s[50:51], 0, v[44:45]
	v_lshl_add_u64 v[78:79], s[52:53], 0, v[44:45]
	v_lshl_add_u64 v[80:81], s[54:55], 0, v[44:45]
	v_lshl_add_u64 v[82:83], s[56:57], 0, v[44:45]
	s_mov_b32 s66, s2
	s_branch .LBB0_103

.LBB0_178:
	s_or_b64 exec, exec, s[0:1]
	v_mov_b64_e32 v[0:1], s[58:59]
	flat_load_dwordx2 v[4:5], v[0:1] offset:144
	flat_load_dwordx2 v[6:7], v[0:1] offset:168
	flat_load_dwordx2 v[8:9], v[0:1] offset:184
	s_waitcnt vmcnt(0)
	s_mov_b64 s[8:9], 0x280000
	v_cmp_gt_u64_e32 vcc, s[8:9], v[2:3]
	s_waitcnt lgkmcnt(0)
	v_readfirstlane_b32 s24, v5
	v_readfirstlane_b32 s25, v4
	v_readfirstlane_b32 s28, v7
	v_readfirstlane_b32 s29, v6
	v_readfirstlane_b32 s11, v9
	v_readfirstlane_b32 s10, v8
	s_and_saveexec_b64 s[12:13], vcc
	s_cbranch_execz .LBB0_211
	s_mov_b64 s[14:15], 0
	s_mov_b32 s33, 0xcccccccd
	v_mov_b32_e32 v1, 0
	s_movk_i32 s44, 0x1fff
	s_movk_i32 s45, 0xffa0
	s_movk_i32 s46, 0x60
	s_movk_i32 s47, 0x1000
	s_movk_i32 s48, 0x7fff
	s_mov_b64 s[16:17], 0x27ffff
	s_branch .LBB0_185

.LBB0_214:
	s_cmpk_gt_i32 s4, 0x7ff
	s_mov_b64 s[0:1], -1
	s_cbranch_scc0 .LBB0_240
	s_cmpk_gt_u32 s4, 0xfff
	s_cbranch_scc0 .LBB0_237
	s_cmpk_gt_u32 s4, 0x17ff
	s_cbranch_scc0 .LBB0_234
	s_cmpk_gt_u32 s4, 0x185f
	s_cbranch_scc0 .LBB0_231
	s_cmpk_gt_u32 s4, 0x18bf
	s_cbranch_scc0 .LBB0_228
	s_cmpk_gt_u32 s4, 0x191f
	s_cbranch_scc0 .LBB0_225
	s_cmpk_gt_u32 s4, 0x197f
	s_cbranch_scc0 .LBB0_222
	v_readlane_b32 s0, v255, 10
	v_readlane_b32 s1, v255, 11
	s_and_b32 s11, s16, 0x7c0
	v_bitop3_b32 v19, s11, v4, v11 bitop3:0xde
	v_mov_b64_e32 v[20:21], s[0:1]
	flat_load_dwordx2 v[20:21], v[20:21] offset:176
	s_waitcnt vmcnt(0)
	s_and_b32 s10, s14, 0xe0
	v_mov_b32_e32 v23, v1
	v_lshlrev_b32_e32 v22, 10, v19
	s_lshl_b32 s6, s10, 2
	s_waitcnt lgkmcnt(0)
	v_readfirstlane_b32 s1, v21
	v_readfirstlane_b32 s0, v20
	s_nop 1
	v_lshl_add_u64 v[20:21], s[0:1], 0, v[22:23]
	v_lshl_add_u64 v[20:21], v[20:21], 0, s[6:7]
	v_lshl_add_u64 v[20:21], v[20:21], 0, v[0:1]
	v_add_co_u32_e32 v22, vcc, s23, v20
	s_or_b32 s0, s10, 0x1a00
	s_nop 0
	v_addc_co_u32_e32 v23, vcc, 0, v21, vcc
	v_add_co_u32_e32 v24, vcc, s24, v20
	s_xor_b32 s1, s11, 0x400
	s_nop 0
	v_addc_co_u32_e32 v25, vcc, 0, v21, vcc
	v_add_co_u32_e32 v26, vcc, s25, v20
	s_lshl_b32 s6, s1, 1
	s_nop 0
	v_addc_co_u32_e32 v27, vcc, 0, v21, vcc
	v_add_co_u32_e32 v28, vcc, s28, v20
	s_nop 1
	v_addc_co_u32_e32 v29, vcc, 0, v21, vcc
	v_add_co_u32_e32 v30, vcc, s29, v20
	s_nop 1
	v_addc_co_u32_e32 v31, vcc, 0, v21, vcc
	v_add_co_u32_e32 v32, vcc, s33, v20
	s_nop 1
	v_addc_co_u32_e32 v33, vcc, 0, v21, vcc
	v_add_co_u32_e32 v34, vcc, s36, v20
	s_nop 1
	v_addc_co_u32_e32 v35, vcc, 0, v21, vcc
	v_add_co_u32_e32 v36, vcc, s37, v20
	s_nop 1
	v_addc_co_u32_e32 v37, vcc, 0, v21, vcc
	v_add_co_u32_e32 v38, vcc, s40, v20
	s_nop 1
	v_addc_co_u32_e32 v39, vcc, 0, v21, vcc
	v_add_co_u32_e32 v40, vcc, s41, v20
	s_nop 1
	v_addc_co_u32_e32 v41, vcc, 0, v21, vcc
	v_add_co_u32_e32 v42, vcc, s42, v20
	s_nop 1
	v_addc_co_u32_e32 v43, vcc, 0, v21, vcc
	v_add_co_u32_e32 v44, vcc, s43, v20
	flat_load_dword v19, v[20:21] nt
	flat_load_dword v46, v[20:21] offset:2048 nt
	flat_load_dword v47, v[22:23] nt
	flat_load_dword v48, v[22:23] offset:2048 nt
	flat_load_dword v49, v[24:25] nt
	flat_load_dword v50, v[24:25] offset:2048 nt
	flat_load_dword v51, v[26:27] nt
	s_nop 0
	flat_load_dword v26, v[26:27] offset:2048 nt
	s_nop 0
	flat_load_dword v27, v[28:29] nt
	s_nop 0
	flat_load_dword v28, v[28:29] offset:2048 nt
	s_nop 0
	flat_load_dword v29, v[30:31] nt
	s_nop 0
	flat_load_dword v30, v[30:31] offset:2048 nt
	s_nop 0
	flat_load_dword v31, v[32:33] nt
	s_nop 0
	flat_load_dword v32, v[32:33] offset:2048 nt
	s_nop 0
	flat_load_dword v33, v[34:35] nt
	s_nop 0
	flat_load_dword v34, v[34:35] offset:2048 nt
	s_nop 0
	flat_load_dword v35, v[36:37] nt
	s_nop 0
	flat_load_dword v36, v[36:37] offset:2048 nt
	s_nop 0
	flat_load_dword v37, v[38:39] nt
	s_nop 0
	flat_load_dword v38, v[38:39] offset:2048 nt
	s_nop 0
	flat_load_dword v39, v[40:41] nt
	s_nop 0
	flat_load_dword v40, v[40:41] offset:2048 nt
	s_nop 0
	flat_load_dword v41, v[42:43] nt
	s_nop 0
	flat_load_dword v42, v[42:43] offset:2048 nt
	v_addc_co_u32_e32 v45, vcc, 0, v21, vcc
	v_add_co_u32_e32 v22, vcc, s44, v20
	s_nop 1
	v_addc_co_u32_e32 v23, vcc, 0, v21, vcc
	v_add_co_u32_e32 v24, vcc, s45, v20
	s_nop 1
	v_addc_co_u32_e32 v25, vcc, 0, v21, vcc
	v_add_co_u32_e32 v20, vcc, s46, v20
	s_nop 1
	v_addc_co_u32_e32 v21, vcc, 0, v21, vcc
	flat_load_dword v43, v[44:45] nt
	s_nop 0
	flat_load_dword v44, v[44:45] offset:2048 nt
	s_nop 0
	flat_load_dword v45, v[22:23] nt
	s_nop 0
	flat_load_dword v22, v[22:23] offset:2048 nt
	s_nop 0
	flat_load_dword v23, v[24:25] nt
	s_nop 0
	flat_load_dword v24, v[24:25] offset:2048 nt
	s_nop 0
	flat_load_dword v25, v[20:21] nt
	s_nop 0
	flat_load_dword v20, v[20:21] offset:2048 nt
	s_waitcnt vmcnt(0) lgkmcnt(0)
	ds_write2_b32 v5, v19, v46 offset1:66
	ds_write2_b32 v5, v47, v48 offset0:132 offset1:198
	ds_write2_b32 v12, v49, v50 offset0:8 offset1:74
	ds_write2_b32 v12, v51, v26 offset0:140 offset1:206
	ds_write2_b32 v13, v27, v28 offset0:16 offset1:82
	ds_write2_b32 v13, v29, v30 offset0:148 offset1:214
	ds_write2_b32 v14, v31, v32 offset0:24 offset1:90
	ds_write2_b32 v14, v33, v34 offset0:156 offset1:222
	ds_write2_b32 v15, v35, v36 offset0:32 offset1:98
	ds_write2_b32 v15, v37, v38 offset0:164 offset1:230
	ds_write2_b32 v16, v39, v40 offset0:40 offset1:106
	ds_write2_b32 v16, v41, v42 offset0:172 offset1:238
	ds_write2_b32 v17, v43, v44 offset0:48 offset1:114
	ds_write2_b32 v17, v45, v22 offset0:180 offset1:246
	ds_write2_b32 v18, v23, v24 offset0:56 offset1:122
	ds_write2_b32 v18, v25, v20 offset0:188 offset1:254
	s_waitcnt lgkmcnt(0)
	ds_read2_b32 v[20:21], v7 offset1:33
	s_waitcnt lgkmcnt(0)
	s_nop 1
	v_cvt_pk_bf16_f32 v20, v20, v21
	ds_read2_b32 v[22:23], v7 offset0:66 offset1:99
	v_or_b32_e32 v19, s0, v6
	s_waitcnt lgkmcnt(0)
	s_nop 1
	v_cvt_pk_bf16_f32 v21, v22, v23
	ds_read2_b32 v[22:23], v7 offset0:132 offset1:165
	v_mov_b32_e32 v25, v1
	v_lshlrev_b32_e32 v24, 12, v19
	v_lshl_add_u64 v[28:29], v[2:3], 0, s[6:7]
	s_waitcnt lgkmcnt(0)
	s_nop 1
	v_cvt_pk_bf16_f32 v22, v22, v23
	ds_read2_b32 v[26:27], v7 offset0:198 offset1:231
	s_waitcnt lgkmcnt(0)
	s_nop 1
	v_cvt_pk_bf16_f32 v23, v26, v27
	v_lshl_add_u64 v[24:25], v[28:29], 0, v[24:25]
	ds_read2_b32 v[26:27], v7 offset0:8 offset1:41
	global_store_dwordx4 v[24:25], v[20:23], off
	v_or_b32_e32 v19, s0, v8
	s_waitcnt lgkmcnt(0)
	s_nop 1
	v_cvt_pk_bf16_f32 v20, v26, v27
	ds_read2_b32 v[22:23], v7 offset0:74 offset1:107
	s_waitcnt lgkmcnt(0)
	s_nop 1
	v_cvt_pk_bf16_f32 v21, v22, v23
	ds_read2_b32 v[22:23], v7 offset0:140 offset1:173
	v_mov_b32_e32 v27, v1
	v_lshlrev_b32_e32 v26, 12, v19
	s_waitcnt lgkmcnt(0)
	s_nop 1
	v_cvt_pk_bf16_f32 v22, v22, v23
	ds_read2_b32 v[24:25], v7 offset0:206 offset1:239
	s_waitcnt lgkmcnt(0)
	s_nop 1
	v_cvt_pk_bf16_f32 v23, v24, v25
	v_lshl_add_u64 v[26:27], v[28:29], 0, v[26:27]
	ds_read2_b32 v[24:25], v7 offset0:16 offset1:49
	global_store_dwordx4 v[26:27], v[20:23], off
	v_or_b32_e32 v19, s0, v9
	v_mov_b32_e32 v27, v1
	s_waitcnt lgkmcnt(0)
	s_nop 1
	v_cvt_pk_bf16_f32 v20, v24, v25
	ds_read2_b32 v[22:23], v7 offset0:82 offset1:115
	s_waitcnt lgkmcnt(0)
	s_nop 1
	v_cvt_pk_bf16_f32 v21, v22, v23
	ds_read2_b32 v[22:23], v7 offset0:148 offset1:181
	v_lshlrev_b32_e32 v26, 12, v19
	s_waitcnt lgkmcnt(0)
	s_nop 1
	v_cvt_pk_bf16_f32 v22, v22, v23
	ds_read2_b32 v[24:25], v7 offset0:214 offset1:247
	s_waitcnt lgkmcnt(0)
	s_nop 1
	v_cvt_pk_bf16_f32 v23, v24, v25
	v_lshl_add_u64 v[26:27], v[28:29], 0, v[26:27]
	ds_read2_b32 v[24:25], v7 offset0:24 offset1:57
	global_store_dwordx4 v[26:27], v[20:23], off
	v_or_b32_e32 v19, s0, v10
	v_mov_b32_e32 v27, v1
	s_waitcnt lgkmcnt(0)
	s_nop 1
	v_cvt_pk_bf16_f32 v20, v24, v25
	ds_read2_b32 v[22:23], v7 offset0:90 offset1:123
	s_waitcnt lgkmcnt(0)
	s_nop 1
	v_cvt_pk_bf16_f32 v21, v22, v23
	ds_read2_b32 v[22:23], v7 offset0:156 offset1:189
	s_waitcnt lgkmcnt(0)
	s_nop 1
	v_cvt_pk_bf16_f32 v22, v22, v23
	ds_read2_b32 v[24:25], v7 offset0:222 offset1:255
	v_lshlrev_b32_e32 v26, 12, v19
	s_waitcnt lgkmcnt(0)
	s_nop 1
	v_cvt_pk_bf16_f32 v23, v24, v25
	v_lshl_add_u64 v[24:25], v[28:29], 0, v[26:27]
	global_store_dwordx4 v[24:25], v[20:23], off
	s_waitcnt lgkmcnt(0)
	s_mov_b64 s[0:1], 0
.LBB0_222:
	s_andn2_b64 vcc, exec, s[0:1]
	s_cbranch_vccnz .LBB0_224
	v_readlane_b32 s0, v255, 10
	v_readlane_b32 s1, v255, 11
	v_mov_b32_e32 v23, v1
	s_nop 0
	v_mov_b64_e32 v[20:21], s[0:1]
	flat_load_dwordx2 v[20:21], v[20:21] offset:160
	s_waitcnt vmcnt(0)
	s_add_i32 s0, s4, 0xffe0
	s_and_b32 s1, s0, 0xff
	s_mulk_i32 s1, 0xab
	s_bfe_u32 s10, s1, 0x70009
	s_mul_i32 s1, s10, 3
	v_lshl_or_b32 v19, s10, 6, v4
	s_sub_i32 s0, s0, s1
	v_mul_u32_u24_e32 v19, 0x60, v19
	s_lshl_b32 s0, s0, 5
	v_lshlrev_b32_e32 v22, 2, v19
	s_and_b32 s11, s0, 0xe0
	s_lshl_b32 s6, s11, 2
	s_addk_i32 s11, 0x1960
	s_waitcnt lgkmcnt(0)
	v_readfirstlane_b32 s1, v21
	v_readfirstlane_b32 s0, v20
	s_nop 1
	v_lshl_add_u64 v[20:21], s[0:1], 0, v[22:23]
	v_lshl_add_u64 v[20:21], v[20:21], 0, s[6:7]
	v_lshl_add_u64 v[20:21], v[20:21], 0, v[0:1]
	v_add_co_u32_e32 v24, vcc, s47, v20
	v_lshl_add_u64 v[22:23], v[20:21], 0, s[8:9]
	s_nop 0
	v_addc_co_u32_e32 v25, vcc, 0, v21, vcc
	v_add_co_u32_e32 v26, vcc, s48, v20
	s_lshl_b32 s6, s10, 7
	s_nop 0
	v_addc_co_u32_e32 v27, vcc, 0, v21, vcc
	v_add_co_u32_e32 v28, vcc, s49, v20
	s_nop 1
	v_addc_co_u32_e32 v29, vcc, 0, v21, vcc
	v_add_co_u32_e32 v30, vcc, s50, v20
	s_nop 1
	v_addc_co_u32_e32 v31, vcc, 0, v21, vcc
	v_add_co_u32_e32 v32, vcc, s51, v20
	s_nop 1
	v_addc_co_u32_e32 v33, vcc, 0, v21, vcc
	v_add_co_u32_e32 v20, vcc, s52, v20
	s_nop 1
	v_addc_co_u32_e32 v21, vcc, 0, v21, vcc
	flat_load_dword v19, v[24:25] nt
	s_nop 0
	flat_load_dword v24, v[22:23] offset:768 nt
	flat_load_dword v25, v[22:23] offset:1536 nt
	flat_load_dword v34, v[22:23] offset:2304 nt
	flat_load_dword v35, v[22:23] offset:3072 nt
	flat_load_dword v36, v[26:27] offset:512 nt
	flat_load_dword v37, v[26:27] offset:1280 nt
	s_nop 0
	flat_load_dword v22, v[22:23] offset:3840 nt
	s_nop 0
	flat_load_dword v23, v[26:27] offset:2048 nt
	flat_load_dword v38, v[26:27] offset:2816 nt
	s_nop 0
	flat_load_dword v26, v[26:27] offset:3584 nt
	s_nop 0
	flat_load_dword v27, v[28:29] offset:256 nt
	flat_load_dword v39, v[28:29] offset:1024 nt
	flat_load_dword v40, v[28:29] offset:1792 nt
	flat_load_dword v41, v[28:29] offset:2560 nt
	s_nop 0
	flat_load_dword v28, v[28:29] offset:3328 nt
	s_nop 0
	flat_load_dword v29, v[30:31] nt
	flat_load_dword v42, v[30:31] offset:768 nt
	flat_load_dword v43, v[30:31] offset:1536 nt
	flat_load_dword v44, v[30:31] offset:2304 nt
	flat_load_dword v45, v[30:31] offset:3072 nt
	s_nop 0
	flat_load_dword v30, v[30:31] offset:3840 nt
	s_nop 0
	flat_load_dword v31, v[32:33] offset:512 nt
	flat_load_dword v46, v[32:33] offset:1280 nt
	flat_load_dword v47, v[32:33] offset:2048 nt
	flat_load_dword v48, v[32:33] offset:2816 nt
	s_nop 0
	flat_load_dword v32, v[32:33] offset:3584 nt
	s_nop 0
	flat_load_dword v33, v[20:21] offset:256 nt
	flat_load_dword v49, v[20:21] offset:1024 nt
	flat_load_dword v50, v[20:21] offset:1792 nt
	flat_load_dword v51, v[20:21] offset:2560 nt
	s_nop 0
	flat_load_dword v20, v[20:21] offset:3328 nt
	s_waitcnt vmcnt(0) lgkmcnt(0)
	ds_write2_b32 v5, v19, v24 offset1:66
	ds_write2_b32 v5, v25, v34 offset0:132 offset1:198
	ds_write2_b32 v12, v35, v22 offset0:8 offset1:74
	ds_write2_b32 v12, v36, v37 offset0:140 offset1:206
	ds_write2_b32 v13, v23, v38 offset0:16 offset1:82
	ds_write2_b32 v13, v26, v27 offset0:148 offset1:214
	ds_write2_b32 v14, v39, v40 offset0:24 offset1:90
	ds_write2_b32 v14, v41, v28 offset0:156 offset1:222
	ds_write2_b32 v15, v29, v42 offset0:32 offset1:98
	ds_write2_b32 v15, v43, v44 offset0:164 offset1:230
	ds_write2_b32 v16, v45, v30 offset0:40 offset1:106
	ds_write2_b32 v16, v31, v46 offset0:172 offset1:238
	ds_write2_b32 v17, v47, v48 offset0:48 offset1:114
	ds_write2_b32 v17, v32, v33 offset0:180 offset1:246
	ds_write2_b32 v18, v49, v50 offset0:56 offset1:122
	ds_write2_b32 v18, v51, v20 offset0:188 offset1:254
	s_waitcnt lgkmcnt(0)
	ds_read2_b32 v[20:21], v7 offset1:33
	s_waitcnt lgkmcnt(0)
	s_nop 1
	v_cvt_pk_bf16_f32 v20, v20, v21
	ds_read2_b32 v[22:23], v7 offset0:66 offset1:99
	v_or_b32_e32 v19, s11, v6
	s_waitcnt lgkmcnt(0)
	s_nop 1
	v_cvt_pk_bf16_f32 v21, v22, v23
	ds_read2_b32 v[22:23], v7 offset0:132 offset1:165
	v_mov_b32_e32 v27, v1
	v_lshlrev_b32_e32 v26, 12, v19
	v_lshl_add_u64 v[28:29], v[2:3], 0, s[6:7]
	s_waitcnt lgkmcnt(0)
	s_nop 1
	v_cvt_pk_bf16_f32 v22, v22, v23
	ds_read2_b32 v[24:25], v7 offset0:198 offset1:231
	s_waitcnt lgkmcnt(0)
	s_nop 1
	v_cvt_pk_bf16_f32 v23, v24, v25
	v_lshl_add_u64 v[26:27], v[28:29], 0, v[26:27]
	ds_read2_b32 v[24:25], v7 offset0:8 offset1:41
	global_store_dwordx4 v[26:27], v[20:23], off
	v_or_b32_e32 v19, s11, v8
	v_mov_b32_e32 v27, v1
	s_waitcnt lgkmcnt(0)
	s_nop 1
	v_cvt_pk_bf16_f32 v20, v24, v25
	ds_read2_b32 v[22:23], v7 offset0:74 offset1:107
	s_waitcnt lgkmcnt(0)
	s_nop 1
	v_cvt_pk_bf16_f32 v21, v22, v23
	ds_read2_b32 v[22:23], v7 offset0:140 offset1:173
	v_lshlrev_b32_e32 v26, 12, v19
	s_waitcnt lgkmcnt(0)
	s_nop 1
	v_cvt_pk_bf16_f32 v22, v22, v23
	ds_read2_b32 v[24:25], v7 offset0:206 offset1:239
	s_waitcnt lgkmcnt(0)
	s_nop 1
	v_cvt_pk_bf16_f32 v23, v24, v25
	v_lshl_add_u64 v[26:27], v[28:29], 0, v[26:27]
	ds_read2_b32 v[24:25], v7 offset0:16 offset1:49
	global_store_dwordx4 v[26:27], v[20:23], off
	v_or_b32_e32 v19, s11, v9
	v_mov_b32_e32 v27, v1
	s_waitcnt lgkmcnt(0)
	s_nop 1
	v_cvt_pk_bf16_f32 v20, v24, v25
	ds_read2_b32 v[22:23], v7 offset0:82 offset1:115
	s_waitcnt lgkmcnt(0)
	s_nop 1
	v_cvt_pk_bf16_f32 v21, v22, v23
	ds_read2_b32 v[22:23], v7 offset0:148 offset1:181
	v_lshlrev_b32_e32 v26, 12, v19
	s_waitcnt lgkmcnt(0)
	s_nop 1
	v_cvt_pk_bf16_f32 v22, v22, v23
	ds_read2_b32 v[24:25], v7 offset0:214 offset1:247
	s_waitcnt lgkmcnt(0)
	s_nop 1
	v_cvt_pk_bf16_f32 v23, v24, v25
	v_lshl_add_u64 v[26:27], v[28:29], 0, v[26:27]
	ds_read2_b32 v[24:25], v7 offset0:24 offset1:57
	global_store_dwordx4 v[26:27], v[20:23], off
	v_or_b32_e32 v19, s11, v10
	v_mov_b32_e32 v27, v1
	s_waitcnt lgkmcnt(0)
	s_nop 1
	v_cvt_pk_bf16_f32 v20, v24, v25
	ds_read2_b32 v[22:23], v7 offset0:90 offset1:123
	s_waitcnt lgkmcnt(0)
	s_nop 1
	v_cvt_pk_bf16_f32 v21, v22, v23
	ds_read2_b32 v[22:23], v7 offset0:156 offset1:189
	s_waitcnt lgkmcnt(0)
	s_nop 1
	v_cvt_pk_bf16_f32 v22, v22, v23
	ds_read2_b32 v[24:25], v7 offset0:222 offset1:255
	v_lshlrev_b32_e32 v26, 12, v19
	s_waitcnt lgkmcnt(0)
	s_nop 1
	v_cvt_pk_bf16_f32 v23, v24, v25
	v_lshl_add_u64 v[24:25], v[28:29], 0, v[26:27]
	global_store_dwordx4 v[24:25], v[20:23], off
	s_waitcnt lgkmcnt(0)

.LBB0_225:
	s_andn2_b64 vcc, exec, s[0:1]
	s_cbranch_vccnz .LBB0_227
	v_readlane_b32 s0, v255, 10
	v_readlane_b32 s1, v255, 11
	v_mov_b32_e32 v23, v1
	s_nop 0
	v_mov_b64_e32 v[20:21], s[0:1]
	flat_load_dwordx2 v[20:21], v[20:21] offset:160
	s_waitcnt vmcnt(0)
	s_add_i32 s0, s4, 64
	s_and_b32 s1, s0, 0xff
	s_mulk_i32 s1, 0xab
	s_bfe_u32 s10, s1, 0x70009
	s_mul_i32 s1, s10, 3
	v_lshl_or_b32 v19, s10, 6, v4
	s_sub_i32 s0, s0, s1
	v_mul_u32_u24_e32 v19, 0x60, v19
	s_lshl_b32 s0, s0, 5
	v_lshlrev_b32_e32 v22, 2, v19
	s_and_b32 s11, s0, 0xe0
	s_lshl_b32 s6, s11, 2
	s_waitcnt lgkmcnt(0)
	v_readfirstlane_b32 s1, v21
	v_readfirstlane_b32 s0, v20
	s_nop 1
	v_lshl_add_u64 v[20:21], s[0:1], 0, v[22:23]
	v_lshl_add_u64 v[20:21], v[20:21], 0, s[6:7]
	v_lshl_add_u64 v[20:21], v[20:21], 0, v[0:1]
	v_add_co_u32_e32 v22, vcc, s23, v20
	s_or_b32 s0, s11, 0x1900
	s_nop 0
	v_addc_co_u32_e32 v23, vcc, 0, v21, vcc
	v_add_co_u32_e32 v24, vcc, s24, v20
	s_lshl_b32 s6, s10, 7
	s_nop 0
	v_addc_co_u32_e32 v25, vcc, 0, v21, vcc
	v_add_co_u32_e32 v26, vcc, s25, v20
	s_nop 1
	v_addc_co_u32_e32 v27, vcc, 0, v21, vcc
	v_add_co_u32_e32 v28, vcc, s28, v20
	s_nop 1
	v_addc_co_u32_e32 v29, vcc, 0, v21, vcc
	v_add_co_u32_e32 v30, vcc, s29, v20
	s_nop 1
	v_addc_co_u32_e32 v31, vcc, 0, v21, vcc
	flat_load_dword v19, v[20:21] nt
	flat_load_dword v32, v[20:21] offset:768 nt
	flat_load_dword v33, v[20:21] offset:1536 nt
	flat_load_dword v34, v[20:21] offset:2304 nt
	flat_load_dword v35, v[20:21] offset:3072 nt
	s_nop 0
	flat_load_dword v20, v[20:21] offset:3840 nt
	s_nop 0
	flat_load_dword v21, v[22:23] offset:512 nt
	flat_load_dword v36, v[22:23] offset:1280 nt
	flat_load_dword v37, v[22:23] offset:2048 nt
	flat_load_dword v38, v[22:23] offset:2816 nt
	s_nop 0
	flat_load_dword v22, v[22:23] offset:3584 nt
	s_nop 0
	flat_load_dword v23, v[24:25] offset:256 nt
	flat_load_dword v39, v[24:25] offset:1024 nt
	flat_load_dword v40, v[24:25] offset:1792 nt
	flat_load_dword v41, v[24:25] offset:2560 nt
	s_nop 0
	flat_load_dword v24, v[24:25] offset:3328 nt
	s_nop 0
	flat_load_dword v25, v[26:27] nt
	flat_load_dword v42, v[26:27] offset:768 nt
	flat_load_dword v43, v[26:27] offset:1536 nt
	flat_load_dword v44, v[26:27] offset:2304 nt
	flat_load_dword v45, v[26:27] offset:3072 nt
	s_nop 0
	flat_load_dword v26, v[26:27] offset:3840 nt
	s_nop 0
	flat_load_dword v27, v[28:29] offset:512 nt
	flat_load_dword v46, v[28:29] offset:1280 nt
	flat_load_dword v47, v[28:29] offset:2048 nt
	flat_load_dword v48, v[28:29] offset:2816 nt
	s_nop 0
	flat_load_dword v28, v[28:29] offset:3584 nt
	s_nop 0
	flat_load_dword v29, v[30:31] offset:256 nt
	flat_load_dword v49, v[30:31] offset:1024 nt
	flat_load_dword v50, v[30:31] offset:1792 nt
	flat_load_dword v51, v[30:31] offset:2560 nt
	s_nop 0
	flat_load_dword v30, v[30:31] offset:3328 nt
	s_waitcnt vmcnt(0) lgkmcnt(0)
	ds_write2_b32 v5, v19, v32 offset1:66
	ds_write2_b32 v5, v33, v34 offset0:132 offset1:198
	ds_write2_b32 v12, v35, v20 offset0:8 offset1:74
	ds_write2_b32 v12, v21, v36 offset0:140 offset1:206
	ds_write2_b32 v13, v37, v38 offset0:16 offset1:82
	ds_write2_b32 v13, v22, v23 offset0:148 offset1:214
	ds_write2_b32 v14, v39, v40 offset0:24 offset1:90
	ds_write2_b32 v14, v41, v24 offset0:156 offset1:222
	ds_write2_b32 v15, v25, v42 offset0:32 offset1:98
	ds_write2_b32 v15, v43, v44 offset0:164 offset1:230
	ds_write2_b32 v16, v45, v26 offset0:40 offset1:106
	ds_write2_b32 v16, v27, v46 offset0:172 offset1:238
	ds_write2_b32 v17, v47, v48 offset0:48 offset1:114
	ds_write2_b32 v17, v28, v29 offset0:180 offset1:246
	ds_write2_b32 v18, v49, v50 offset0:56 offset1:122
	ds_write2_b32 v18, v51, v30 offset0:188 offset1:254
	s_waitcnt lgkmcnt(0)
	ds_read2_b32 v[20:21], v7 offset1:33
	s_waitcnt lgkmcnt(0)
	s_nop 1
	v_cvt_pk_bf16_f32 v20, v20, v21
	ds_read2_b32 v[22:23], v7 offset0:66 offset1:99
	v_or_b32_e32 v19, s0, v6
	s_waitcnt lgkmcnt(0)
	s_nop 1
	v_cvt_pk_bf16_f32 v21, v22, v23
	ds_read2_b32 v[22:23], v7 offset0:132 offset1:165
	v_mov_b32_e32 v27, v1
	v_lshlrev_b32_e32 v26, 12, v19
	v_lshl_add_u64 v[28:29], v[2:3], 0, s[6:7]
	s_waitcnt lgkmcnt(0)
	s_nop 1
	v_cvt_pk_bf16_f32 v22, v22, v23
	ds_read2_b32 v[24:25], v7 offset0:198 offset1:231
	s_waitcnt lgkmcnt(0)
	s_nop 1
	v_cvt_pk_bf16_f32 v23, v24, v25
	v_lshl_add_u64 v[26:27], v[28:29], 0, v[26:27]
	ds_read2_b32 v[24:25], v7 offset0:8 offset1:41
	global_store_dwordx4 v[26:27], v[20:23], off
	v_or_b32_e32 v19, s0, v8
	v_mov_b32_e32 v27, v1
	s_waitcnt lgkmcnt(0)
	s_nop 1
	v_cvt_pk_bf16_f32 v20, v24, v25
	ds_read2_b32 v[22:23], v7 offset0:74 offset1:107
	s_waitcnt lgkmcnt(0)
	s_nop 1
	v_cvt_pk_bf16_f32 v21, v22, v23
	ds_read2_b32 v[22:23], v7 offset0:140 offset1:173
	v_lshlrev_b32_e32 v26, 12, v19
	s_waitcnt lgkmcnt(0)
	s_nop 1
	v_cvt_pk_bf16_f32 v22, v22, v23
	ds_read2_b32 v[24:25], v7 offset0:206 offset1:239
	s_waitcnt lgkmcnt(0)
	s_nop 1
	v_cvt_pk_bf16_f32 v23, v24, v25
	v_lshl_add_u64 v[26:27], v[28:29], 0, v[26:27]
	ds_read2_b32 v[24:25], v7 offset0:16 offset1:49
	global_store_dwordx4 v[26:27], v[20:23], off
	v_or_b32_e32 v19, s0, v9
	v_mov_b32_e32 v27, v1
	s_waitcnt lgkmcnt(0)
	s_nop 1
	v_cvt_pk_bf16_f32 v20, v24, v25
	ds_read2_b32 v[22:23], v7 offset0:82 offset1:115
	s_waitcnt lgkmcnt(0)
	s_nop 1
	v_cvt_pk_bf16_f32 v21, v22, v23
	ds_read2_b32 v[22:23], v7 offset0:148 offset1:181
	v_lshlrev_b32_e32 v26, 12, v19
	s_waitcnt lgkmcnt(0)
	s_nop 1
	v_cvt_pk_bf16_f32 v22, v22, v23
	ds_read2_b32 v[24:25], v7 offset0:214 offset1:247
	s_waitcnt lgkmcnt(0)
	s_nop 1
	v_cvt_pk_bf16_f32 v23, v24, v25
	v_lshl_add_u64 v[26:27], v[28:29], 0, v[26:27]
	ds_read2_b32 v[24:25], v7 offset0:24 offset1:57
	global_store_dwordx4 v[26:27], v[20:23], off
	v_or_b32_e32 v19, s0, v10
	v_mov_b32_e32 v27, v1
	s_waitcnt lgkmcnt(0)
	s_nop 1
	v_cvt_pk_bf16_f32 v20, v24, v25
	ds_read2_b32 v[22:23], v7 offset0:90 offset1:123
	s_waitcnt lgkmcnt(0)
	s_nop 1
	v_cvt_pk_bf16_f32 v21, v22, v23
	ds_read2_b32 v[22:23], v7 offset0:156 offset1:189
	s_waitcnt lgkmcnt(0)
	s_nop 1
	v_cvt_pk_bf16_f32 v22, v22, v23
	ds_read2_b32 v[24:25], v7 offset0:222 offset1:255
	v_lshlrev_b32_e32 v26, 12, v19
	s_waitcnt lgkmcnt(0)
	s_nop 1
	v_cvt_pk_bf16_f32 v23, v24, v25
	v_lshl_add_u64 v[24:25], v[28:29], 0, v[26:27]
	global_store_dwordx4 v[24:25], v[20:23], off
	s_waitcnt lgkmcnt(0)

.LBB0_228:
	s_andn2_b64 vcc, exec, s[0:1]
	s_cbranch_vccnz .LBB0_230
	v_readlane_b32 s0, v255, 10
	v_readlane_b32 s1, v255, 11
	v_mov_b32_e32 v23, v1
	s_nop 0
	v_mov_b64_e32 v[20:21], s[0:1]
	flat_load_dwordx2 v[20:21], v[20:21] offset:136
	s_waitcnt vmcnt(0)
	s_add_i32 s0, s4, 0xffa0
	s_and_b32 s1, s0, 0xff
	s_mulk_i32 s1, 0xab
	s_bfe_u32 s10, s1, 0x70009
	s_mul_i32 s1, s10, 3
	v_lshl_or_b32 v19, s10, 6, v4
	s_sub_i32 s0, s0, s1
	v_mul_u32_u24_e32 v19, 0x60, v19
	s_lshl_b32 s0, s0, 5
	v_lshlrev_b32_e32 v22, 2, v19
	s_and_b32 s11, s0, 0xe0
	s_lshl_b32 s6, s11, 2
	s_addk_i32 s11, 0x1860
	s_waitcnt lgkmcnt(0)
	v_readfirstlane_b32 s1, v21
	v_readfirstlane_b32 s0, v20
	s_nop 1
	v_lshl_add_u64 v[20:21], s[0:1], 0, v[22:23]
	v_lshl_add_u64 v[20:21], v[20:21], 0, s[6:7]
	v_lshl_add_u64 v[20:21], v[20:21], 0, v[0:1]
	v_add_co_u32_e32 v24, vcc, s47, v20
	v_lshl_add_u64 v[22:23], v[20:21], 0, s[8:9]
	s_nop 0
	v_addc_co_u32_e32 v25, vcc, 0, v21, vcc
	v_add_co_u32_e32 v26, vcc, s48, v20
	s_lshl_b32 s6, s10, 7
	s_nop 0
	v_addc_co_u32_e32 v27, vcc, 0, v21, vcc
	v_add_co_u32_e32 v28, vcc, s49, v20
	s_nop 1
	v_addc_co_u32_e32 v29, vcc, 0, v21, vcc
	v_add_co_u32_e32 v30, vcc, s50, v20
	s_nop 1
	v_addc_co_u32_e32 v31, vcc, 0, v21, vcc
	v_add_co_u32_e32 v32, vcc, s51, v20
	s_nop 1
	v_addc_co_u32_e32 v33, vcc, 0, v21, vcc
	v_add_co_u32_e32 v20, vcc, s52, v20
	s_nop 1
	v_addc_co_u32_e32 v21, vcc, 0, v21, vcc
	flat_load_dword v19, v[24:25] nt
	s_nop 0
	flat_load_dword v24, v[22:23] offset:768 nt
	flat_load_dword v25, v[22:23] offset:1536 nt
	flat_load_dword v34, v[22:23] offset:2304 nt
	flat_load_dword v35, v[22:23] offset:3072 nt
	flat_load_dword v36, v[26:27] offset:512 nt
	flat_load_dword v37, v[26:27] offset:1280 nt
	s_nop 0
	flat_load_dword v22, v[22:23] offset:3840 nt
	s_nop 0
	flat_load_dword v23, v[26:27] offset:2048 nt
	flat_load_dword v38, v[26:27] offset:2816 nt
	s_nop 0
	flat_load_dword v26, v[26:27] offset:3584 nt
	s_nop 0
	flat_load_dword v27, v[28:29] offset:256 nt
	flat_load_dword v39, v[28:29] offset:1024 nt
	flat_load_dword v40, v[28:29] offset:1792 nt
	flat_load_dword v41, v[28:29] offset:2560 nt
	s_nop 0
	flat_load_dword v28, v[28:29] offset:3328 nt
	s_nop 0
	flat_load_dword v29, v[30:31] nt
	flat_load_dword v42, v[30:31] offset:768 nt
	flat_load_dword v43, v[30:31] offset:1536 nt
	flat_load_dword v44, v[30:31] offset:2304 nt
	flat_load_dword v45, v[30:31] offset:3072 nt
	s_nop 0
	flat_load_dword v30, v[30:31] offset:3840 nt
	s_nop 0
	flat_load_dword v31, v[32:33] offset:512 nt
	flat_load_dword v46, v[32:33] offset:1280 nt
	flat_load_dword v47, v[32:33] offset:2048 nt
	flat_load_dword v48, v[32:33] offset:2816 nt
	s_nop 0
	flat_load_dword v32, v[32:33] offset:3584 nt
	s_nop 0
	flat_load_dword v33, v[20:21] offset:256 nt
	flat_load_dword v49, v[20:21] offset:1024 nt
	flat_load_dword v50, v[20:21] offset:1792 nt
	flat_load_dword v51, v[20:21] offset:2560 nt
	s_nop 0
	flat_load_dword v20, v[20:21] offset:3328 nt
	s_waitcnt vmcnt(0) lgkmcnt(0)
	ds_write2_b32 v5, v19, v24 offset1:66
	ds_write2_b32 v5, v25, v34 offset0:132 offset1:198
	ds_write2_b32 v12, v35, v22 offset0:8 offset1:74
	ds_write2_b32 v12, v36, v37 offset0:140 offset1:206
	ds_write2_b32 v13, v23, v38 offset0:16 offset1:82
	ds_write2_b32 v13, v26, v27 offset0:148 offset1:214
	ds_write2_b32 v14, v39, v40 offset0:24 offset1:90
	ds_write2_b32 v14, v41, v28 offset0:156 offset1:222
	ds_write2_b32 v15, v29, v42 offset0:32 offset1:98
	ds_write2_b32 v15, v43, v44 offset0:164 offset1:230
	ds_write2_b32 v16, v45, v30 offset0:40 offset1:106
	ds_write2_b32 v16, v31, v46 offset0:172 offset1:238
	ds_write2_b32 v17, v47, v48 offset0:48 offset1:114
	ds_write2_b32 v17, v32, v33 offset0:180 offset1:246
	ds_write2_b32 v18, v49, v50 offset0:56 offset1:122
	ds_write2_b32 v18, v51, v20 offset0:188 offset1:254
	s_waitcnt lgkmcnt(0)
	ds_read2_b32 v[20:21], v7 offset1:33
	s_waitcnt lgkmcnt(0)
	s_nop 1
	v_cvt_pk_bf16_f32 v20, v20, v21
	ds_read2_b32 v[22:23], v7 offset0:66 offset1:99
	v_or_b32_e32 v19, s11, v6
	s_waitcnt lgkmcnt(0)
	s_nop 1
	v_cvt_pk_bf16_f32 v21, v22, v23
	ds_read2_b32 v[22:23], v7 offset0:132 offset1:165
	v_mov_b32_e32 v27, v1
	v_lshlrev_b32_e32 v26, 12, v19
	v_lshl_add_u64 v[28:29], v[2:3], 0, s[6:7]
	s_waitcnt lgkmcnt(0)
	s_nop 1
	v_cvt_pk_bf16_f32 v22, v22, v23
	ds_read2_b32 v[24:25], v7 offset0:198 offset1:231
	s_waitcnt lgkmcnt(0)
	s_nop 1
	v_cvt_pk_bf16_f32 v23, v24, v25
	v_lshl_add_u64 v[26:27], v[28:29], 0, v[26:27]
	ds_read2_b32 v[24:25], v7 offset0:8 offset1:41
	global_store_dwordx4 v[26:27], v[20:23], off
	v_or_b32_e32 v19, s11, v8
	v_mov_b32_e32 v27, v1
	s_waitcnt lgkmcnt(0)
	s_nop 1
	v_cvt_pk_bf16_f32 v20, v24, v25
	ds_read2_b32 v[22:23], v7 offset0:74 offset1:107
	s_waitcnt lgkmcnt(0)
	s_nop 1
	v_cvt_pk_bf16_f32 v21, v22, v23
	ds_read2_b32 v[22:23], v7 offset0:140 offset1:173
	v_lshlrev_b32_e32 v26, 12, v19
	s_waitcnt lgkmcnt(0)
	s_nop 1
	v_cvt_pk_bf16_f32 v22, v22, v23
	ds_read2_b32 v[24:25], v7 offset0:206 offset1:239
	s_waitcnt lgkmcnt(0)
	s_nop 1
	v_cvt_pk_bf16_f32 v23, v24, v25
	v_lshl_add_u64 v[26:27], v[28:29], 0, v[26:27]
	ds_read2_b32 v[24:25], v7 offset0:16 offset1:49
	global_store_dwordx4 v[26:27], v[20:23], off
	v_or_b32_e32 v19, s11, v9
	v_mov_b32_e32 v27, v1
	s_waitcnt lgkmcnt(0)
	s_nop 1
	v_cvt_pk_bf16_f32 v20, v24, v25
	ds_read2_b32 v[22:23], v7 offset0:82 offset1:115
	s_waitcnt lgkmcnt(0)
	s_nop 1
	v_cvt_pk_bf16_f32 v21, v22, v23
	ds_read2_b32 v[22:23], v7 offset0:148 offset1:181
	v_lshlrev_b32_e32 v26, 12, v19
	s_waitcnt lgkmcnt(0)
	s_nop 1
	v_cvt_pk_bf16_f32 v22, v22, v23
	ds_read2_b32 v[24:25], v7 offset0:214 offset1:247
	s_waitcnt lgkmcnt(0)
	s_nop 1
	v_cvt_pk_bf16_f32 v23, v24, v25
	v_lshl_add_u64 v[26:27], v[28:29], 0, v[26:27]
	ds_read2_b32 v[24:25], v7 offset0:24 offset1:57
	global_store_dwordx4 v[26:27], v[20:23], off
	v_or_b32_e32 v19, s11, v10
	v_mov_b32_e32 v27, v1
	s_waitcnt lgkmcnt(0)
	s_nop 1
	v_cvt_pk_bf16_f32 v20, v24, v25
	ds_read2_b32 v[22:23], v7 offset0:90 offset1:123
	s_waitcnt lgkmcnt(0)
	s_nop 1
	v_cvt_pk_bf16_f32 v21, v22, v23
	ds_read2_b32 v[22:23], v7 offset0:156 offset1:189
	s_waitcnt lgkmcnt(0)
	s_nop 1
	v_cvt_pk_bf16_f32 v22, v22, v23
	ds_read2_b32 v[24:25], v7 offset0:222 offset1:255
	v_lshlrev_b32_e32 v26, 12, v19
	s_waitcnt lgkmcnt(0)
	s_nop 1
	v_cvt_pk_bf16_f32 v23, v24, v25
	v_lshl_add_u64 v[24:25], v[28:29], 0, v[26:27]
	global_store_dwordx4 v[24:25], v[20:23], off
	s_waitcnt lgkmcnt(0)

.LBB0_231:
	s_andn2_b64 vcc, exec, s[0:1]
	s_cbranch_vccnz .LBB0_233
	v_readlane_b32 s0, v255, 10
	v_readlane_b32 s1, v255, 11
	v_mov_b32_e32 v23, v1
	s_nop 0
	v_mov_b64_e32 v[20:21], s[0:1]
	flat_load_dwordx2 v[20:21], v[20:21] offset:136
	s_waitcnt vmcnt(0)
	s_and_b32 s0, s4, 0xff
	s_mulk_i32 s0, 0xab
	s_lshr_b32 s10, s0, 9
	s_mul_i32 s0, s10, 3
	v_lshl_or_b32 v19, s10, 6, v4
	s_sub_i32 s0, s4, s0
	v_mul_u32_u24_e32 v19, 0x60, v19
	s_lshl_b32 s0, s0, 5
	v_lshlrev_b32_e32 v22, 2, v19
	s_and_b32 s11, s0, 0xe0
	s_lshl_b32 s6, s11, 2
	s_waitcnt lgkmcnt(0)
	v_readfirstlane_b32 s1, v21
	v_readfirstlane_b32 s0, v20
	s_nop 1
	v_lshl_add_u64 v[20:21], s[0:1], 0, v[22:23]
	v_lshl_add_u64 v[20:21], v[20:21], 0, s[6:7]
	v_lshl_add_u64 v[20:21], v[20:21], 0, v[0:1]
	v_add_co_u32_e32 v22, vcc, s23, v20
	s_or_b32 s0, s11, 0x1800
	s_nop 0
	v_addc_co_u32_e32 v23, vcc, 0, v21, vcc
	v_add_co_u32_e32 v24, vcc, s24, v20
	s_lshl_b32 s6, s10, 7
	s_nop 0
	v_addc_co_u32_e32 v25, vcc, 0, v21, vcc
	v_add_co_u32_e32 v26, vcc, s25, v20
	s_nop 1
	v_addc_co_u32_e32 v27, vcc, 0, v21, vcc
	v_add_co_u32_e32 v28, vcc, s28, v20
	s_nop 1
	v_addc_co_u32_e32 v29, vcc, 0, v21, vcc
	v_add_co_u32_e32 v30, vcc, s29, v20
	s_nop 1
	v_addc_co_u32_e32 v31, vcc, 0, v21, vcc
	flat_load_dword v19, v[20:21] nt
	flat_load_dword v32, v[20:21] offset:768 nt
	flat_load_dword v33, v[20:21] offset:1536 nt
	flat_load_dword v34, v[20:21] offset:2304 nt
	flat_load_dword v35, v[20:21] offset:3072 nt
	s_nop 0
	flat_load_dword v20, v[20:21] offset:3840 nt
	s_nop 0
	flat_load_dword v21, v[22:23] offset:512 nt
	flat_load_dword v36, v[22:23] offset:1280 nt
	flat_load_dword v37, v[22:23] offset:2048 nt
	flat_load_dword v38, v[22:23] offset:2816 nt
	s_nop 0
	flat_load_dword v22, v[22:23] offset:3584 nt
	s_nop 0
	flat_load_dword v23, v[24:25] offset:256 nt
	flat_load_dword v39, v[24:25] offset:1024 nt
	flat_load_dword v40, v[24:25] offset:1792 nt
	flat_load_dword v41, v[24:25] offset:2560 nt
	s_nop 0
	flat_load_dword v24, v[24:25] offset:3328 nt
	s_nop 0
	flat_load_dword v25, v[26:27] nt
	flat_load_dword v42, v[26:27] offset:768 nt
	flat_load_dword v43, v[26:27] offset:1536 nt
	flat_load_dword v44, v[26:27] offset:2304 nt
	flat_load_dword v45, v[26:27] offset:3072 nt
	s_nop 0
	flat_load_dword v26, v[26:27] offset:3840 nt
	s_nop 0
	flat_load_dword v27, v[28:29] offset:512 nt
	flat_load_dword v46, v[28:29] offset:1280 nt
	flat_load_dword v47, v[28:29] offset:2048 nt
	flat_load_dword v48, v[28:29] offset:2816 nt
	s_nop 0
	flat_load_dword v28, v[28:29] offset:3584 nt
	s_nop 0
	flat_load_dword v29, v[30:31] offset:256 nt
	flat_load_dword v49, v[30:31] offset:1024 nt
	flat_load_dword v50, v[30:31] offset:1792 nt
	flat_load_dword v51, v[30:31] offset:2560 nt
	s_nop 0
	flat_load_dword v30, v[30:31] offset:3328 nt
	s_waitcnt vmcnt(0) lgkmcnt(0)
	ds_write2_b32 v5, v19, v32 offset1:66
	ds_write2_b32 v5, v33, v34 offset0:132 offset1:198
	ds_write2_b32 v12, v35, v20 offset0:8 offset1:74
	ds_write2_b32 v12, v21, v36 offset0:140 offset1:206
	ds_write2_b32 v13, v37, v38 offset0:16 offset1:82
	ds_write2_b32 v13, v22, v23 offset0:148 offset1:214
	ds_write2_b32 v14, v39, v40 offset0:24 offset1:90
	ds_write2_b32 v14, v41, v24 offset0:156 offset1:222
	ds_write2_b32 v15, v25, v42 offset0:32 offset1:98
	ds_write2_b32 v15, v43, v44 offset0:164 offset1:230
	ds_write2_b32 v16, v45, v26 offset0:40 offset1:106
	ds_write2_b32 v16, v27, v46 offset0:172 offset1:238
	ds_write2_b32 v17, v47, v48 offset0:48 offset1:114
	ds_write2_b32 v17, v28, v29 offset0:180 offset1:246
	ds_write2_b32 v18, v49, v50 offset0:56 offset1:122
	ds_write2_b32 v18, v51, v30 offset0:188 offset1:254
	s_waitcnt lgkmcnt(0)
	ds_read2_b32 v[20:21], v7 offset1:33
	s_waitcnt lgkmcnt(0)
	s_nop 1
	v_cvt_pk_bf16_f32 v20, v20, v21
	ds_read2_b32 v[22:23], v7 offset0:66 offset1:99
	v_or_b32_e32 v19, s0, v6
	s_waitcnt lgkmcnt(0)
	s_nop 1
	v_cvt_pk_bf16_f32 v21, v22, v23
	ds_read2_b32 v[22:23], v7 offset0:132 offset1:165
	v_mov_b32_e32 v27, v1
	v_lshlrev_b32_e32 v26, 12, v19
	v_lshl_add_u64 v[28:29], v[2:3], 0, s[6:7]
	s_waitcnt lgkmcnt(0)
	s_nop 1
	v_cvt_pk_bf16_f32 v22, v22, v23
	ds_read2_b32 v[24:25], v7 offset0:198 offset1:231
	s_waitcnt lgkmcnt(0)
	s_nop 1
	v_cvt_pk_bf16_f32 v23, v24, v25
	v_lshl_add_u64 v[26:27], v[28:29], 0, v[26:27]
	ds_read2_b32 v[24:25], v7 offset0:8 offset1:41
	global_store_dwordx4 v[26:27], v[20:23], off
	v_or_b32_e32 v19, s0, v8
	v_mov_b32_e32 v27, v1
	s_waitcnt lgkmcnt(0)
	s_nop 1
	v_cvt_pk_bf16_f32 v20, v24, v25
	ds_read2_b32 v[22:23], v7 offset0:74 offset1:107
	s_waitcnt lgkmcnt(0)
	s_nop 1
	v_cvt_pk_bf16_f32 v21, v22, v23
	ds_read2_b32 v[22:23], v7 offset0:140 offset1:173
	v_lshlrev_b32_e32 v26, 12, v19
	s_waitcnt lgkmcnt(0)
	s_nop 1
	v_cvt_pk_bf16_f32 v22, v22, v23
	ds_read2_b32 v[24:25], v7 offset0:206 offset1:239
	s_waitcnt lgkmcnt(0)
	s_nop 1
	v_cvt_pk_bf16_f32 v23, v24, v25
	v_lshl_add_u64 v[26:27], v[28:29], 0, v[26:27]
	ds_read2_b32 v[24:25], v7 offset0:16 offset1:49
	global_store_dwordx4 v[26:27], v[20:23], off
	v_or_b32_e32 v19, s0, v9
	v_mov_b32_e32 v27, v1
	s_waitcnt lgkmcnt(0)
	s_nop 1
	v_cvt_pk_bf16_f32 v20, v24, v25
	ds_read2_b32 v[22:23], v7 offset0:82 offset1:115
	s_waitcnt lgkmcnt(0)
	s_nop 1
	v_cvt_pk_bf16_f32 v21, v22, v23
	ds_read2_b32 v[22:23], v7 offset0:148 offset1:181
	v_lshlrev_b32_e32 v26, 12, v19
	s_waitcnt lgkmcnt(0)
	s_nop 1
	v_cvt_pk_bf16_f32 v22, v22, v23
	ds_read2_b32 v[24:25], v7 offset0:214 offset1:247
	s_waitcnt lgkmcnt(0)
	s_nop 1
	v_cvt_pk_bf16_f32 v23, v24, v25
	v_lshl_add_u64 v[26:27], v[28:29], 0, v[26:27]
	ds_read2_b32 v[24:25], v7 offset0:24 offset1:57
	global_store_dwordx4 v[26:27], v[20:23], off
	v_or_b32_e32 v19, s0, v10
	v_mov_b32_e32 v27, v1
	s_waitcnt lgkmcnt(0)
	s_nop 1
	v_cvt_pk_bf16_f32 v20, v24, v25
	ds_read2_b32 v[22:23], v7 offset0:90 offset1:123
	s_waitcnt lgkmcnt(0)
	s_nop 1
	v_cvt_pk_bf16_f32 v21, v22, v23
	ds_read2_b32 v[22:23], v7 offset0:156 offset1:189
	s_waitcnt lgkmcnt(0)
	s_nop 1
	v_cvt_pk_bf16_f32 v22, v22, v23
	ds_read2_b32 v[24:25], v7 offset0:222 offset1:255
	v_lshlrev_b32_e32 v26, 12, v19
	s_waitcnt lgkmcnt(0)
	s_nop 1
	v_cvt_pk_bf16_f32 v23, v24, v25
	v_lshl_add_u64 v[24:25], v[28:29], 0, v[26:27]
	global_store_dwordx4 v[24:25], v[20:23], off
	s_waitcnt lgkmcnt(0)

.LBB0_234:
	s_andn2_b64 vcc, exec, s[0:1]
	s_cbranch_vccnz .LBB0_236
	v_readlane_b32 s0, v255, 10
	v_readlane_b32 s1, v255, 11
	v_mov_b32_e32 v23, v1
	s_nop 0
	v_mov_b64_e32 v[20:21], s[0:1]
	flat_load_dwordx2 v[20:21], v[20:21] offset:112
	s_waitcnt vmcnt(0)
	s_add_i32 s1, s4, 0xf000
	s_and_b32 s1, s1, 0xffc0
	v_or_b32_e32 v19, s1, v4
	s_and_b32 s0, s14, 0x7e0
	v_lshlrev_b32_e32 v22, 13, v19
	s_lshl_b32 s6, s0, 2
	s_bitset1_b32 s0, 12
	s_waitcnt lgkmcnt(0)
	v_readfirstlane_b32 s11, v21
	v_readfirstlane_b32 s10, v20
	s_nop 1
	v_lshl_add_u64 v[20:21], s[10:11], 0, v[22:23]
	v_lshl_add_u64 v[20:21], v[20:21], 0, s[6:7]
	v_lshl_add_u64 v[20:21], v[20:21], 0, v[0:1]
	v_add_co_u32_e32 v22, vcc, s28, v20
	s_lshl_b32 s6, s1, 1
	s_nop 0
	v_addc_co_u32_e32 v23, vcc, 0, v21, vcc
	v_add_co_u32_e32 v24, vcc, s37, v20
	s_nop 1
	v_addc_co_u32_e32 v25, vcc, 0, v21, vcc
	v_add_co_u32_e32 v26, vcc, s43, v20
	s_nop 1
	v_addc_co_u32_e32 v27, vcc, 0, v21, vcc
	v_add_co_u32_e32 v28, vcc, s53, v20
	s_nop 1
	v_addc_co_u32_e32 v29, vcc, 0, v21, vcc
	v_add_co_u32_e32 v30, vcc, s54, v20
	s_nop 1
	v_addc_co_u32_e32 v31, vcc, 0, v21, vcc
	v_add_co_u32_e32 v32, vcc, s55, v20
	s_nop 1
	v_addc_co_u32_e32 v33, vcc, 0, v21, vcc
	v_add_co_u32_e32 v34, vcc, s56, v20
	s_nop 1
	v_addc_co_u32_e32 v35, vcc, 0, v21, vcc
	v_add_co_u32_e32 v36, vcc, s57, v20
	s_nop 1
	v_addc_co_u32_e32 v37, vcc, 0, v21, vcc
	v_add_co_u32_e32 v38, vcc, s58, v20
	s_nop 1
	v_addc_co_u32_e32 v39, vcc, 0, v21, vcc
	v_add_co_u32_e32 v40, vcc, s59, v20
	s_nop 1
	v_addc_co_u32_e32 v41, vcc, 0, v21, vcc
	v_add_co_u32_e32 v42, vcc, s60, v20
	s_nop 1
	v_addc_co_u32_e32 v43, vcc, 0, v21, vcc
	v_add_co_u32_e32 v44, vcc, s61, v20
	s_nop 1
	v_addc_co_u32_e32 v45, vcc, 0, v21, vcc
	v_add_co_u32_e32 v46, vcc, s62, v20
	s_nop 1
	v_addc_co_u32_e32 v47, vcc, 0, v21, vcc
	v_add_co_u32_e32 v48, vcc, s63, v20
	s_nop 1
	v_addc_co_u32_e32 v49, vcc, 0, v21, vcc
	v_add_co_u32_e32 v50, vcc, s64, v20
	s_nop 1
	v_addc_co_u32_e32 v51, vcc, 0, v21, vcc
	flat_load_dword v19, v[20:21] nt
	flat_load_dword v52, v[22:23] nt
	flat_load_dword v53, v[24:25] nt
	flat_load_dword v54, v[26:27] nt
	flat_load_dword v55, v[28:29] nt
	flat_load_dword v56, v[30:31] nt
	flat_load_dword v57, v[32:33] nt
	flat_load_dword v58, v[34:35] nt
	flat_load_dword v59, v[36:37] nt
	s_nop 0
	flat_load_dword v38, v[38:39] nt
	s_nop 0
	flat_load_dword v39, v[40:41] nt
	s_nop 0
	flat_load_dword v40, v[42:43] nt
	flat_load_dword v41, v[44:45] nt
	s_nop 0
	flat_load_dword v42, v[46:47] nt
	flat_load_dword v43, v[48:49] nt
	flat_load_dword v44, v[50:51] nt
	v_add_co_u32_e32 v22, vcc, s65, v20
	s_nop 1
	v_addc_co_u32_e32 v23, vcc, 0, v21, vcc
	v_add_co_u32_e32 v24, vcc, s66, v20
	s_nop 1
	v_addc_co_u32_e32 v25, vcc, 0, v21, vcc
	v_add_co_u32_e32 v26, vcc, s67, v20
	s_nop 1
	v_addc_co_u32_e32 v27, vcc, 0, v21, vcc
	v_add_co_u32_e32 v28, vcc, s68, v20
	s_nop 1
	v_addc_co_u32_e32 v29, vcc, 0, v21, vcc
	v_add_co_u32_e32 v30, vcc, s69, v20
	s_nop 1
	v_addc_co_u32_e32 v31, vcc, 0, v21, vcc
	v_add_co_u32_e32 v32, vcc, s70, v20
	s_nop 1
	v_addc_co_u32_e32 v33, vcc, 0, v21, vcc
	v_add_co_u32_e32 v34, vcc, s71, v20
	s_nop 1
	v_addc_co_u32_e32 v35, vcc, 0, v21, vcc
	v_add_co_u32_e32 v36, vcc, s72, v20
	s_nop 1
	v_addc_co_u32_e32 v37, vcc, 0, v21, vcc
	flat_load_dword v45, v[22:23] nt
	flat_load_dword v46, v[24:25] nt
	flat_load_dword v47, v[26:27] nt
	flat_load_dword v48, v[28:29] nt
	flat_load_dword v49, v[30:31] nt
	flat_load_dword v50, v[32:33] nt
	flat_load_dword v51, v[34:35] nt
	s_nop 0
	flat_load_dword v36, v[36:37] nt
	v_add_co_u32_e32 v22, vcc, s73, v20
	s_nop 1
	v_addc_co_u32_e32 v23, vcc, 0, v21, vcc
	v_add_co_u32_e32 v24, vcc, s74, v20
	s_nop 1
	v_addc_co_u32_e32 v25, vcc, 0, v21, vcc
	v_add_co_u32_e32 v26, vcc, s75, v20
	s_nop 1
	v_addc_co_u32_e32 v27, vcc, 0, v21, vcc
	v_add_co_u32_e32 v28, vcc, s76, v20
	s_nop 1
	v_addc_co_u32_e32 v29, vcc, 0, v21, vcc
	v_add_co_u32_e32 v30, vcc, s77, v20
	s_nop 1
	v_addc_co_u32_e32 v31, vcc, 0, v21, vcc
	v_add_co_u32_e32 v32, vcc, s78, v20
	s_nop 1
	v_addc_co_u32_e32 v33, vcc, 0, v21, vcc
	v_add_co_u32_e32 v34, vcc, s79, v20
	s_nop 1
	v_addc_co_u32_e32 v35, vcc, 0, v21, vcc
	v_add_co_u32_e32 v20, vcc, s80, v20
	s_nop 1
	v_addc_co_u32_e32 v21, vcc, 0, v21, vcc
	flat_load_dword v22, v[22:23] nt
	s_nop 0
	flat_load_dword v23, v[24:25] nt
	s_nop 0
	flat_load_dword v24, v[26:27] nt
	flat_load_dword v25, v[28:29] nt
	s_nop 0
	flat_load_dword v26, v[30:31] nt
	flat_load_dword v27, v[32:33] nt
	flat_load_dword v28, v[34:35] nt
	s_nop 0
	flat_load_dword v20, v[20:21] nt
	s_waitcnt vmcnt(0) lgkmcnt(0)
	ds_write2_b32 v5, v19, v52 offset1:66
	ds_write2_b32 v5, v53, v54 offset0:132 offset1:198
	ds_write2_b32 v12, v55, v56 offset0:8 offset1:74
	ds_write2_b32 v12, v57, v58 offset0:140 offset1:206
	ds_write2_b32 v13, v59, v38 offset0:16 offset1:82
	ds_write2_b32 v13, v39, v40 offset0:148 offset1:214
	ds_write2_b32 v14, v41, v42 offset0:24 offset1:90
	ds_write2_b32 v14, v43, v44 offset0:156 offset1:222
	ds_write2_b32 v15, v45, v46 offset0:32 offset1:98
	ds_write2_b32 v15, v47, v48 offset0:164 offset1:230
	ds_write2_b32 v16, v49, v50 offset0:40 offset1:106
	ds_write2_b32 v16, v51, v36 offset0:172 offset1:238
	ds_write2_b32 v17, v22, v23 offset0:48 offset1:114
	ds_write2_b32 v17, v24, v25 offset0:180 offset1:246
	ds_write2_b32 v18, v26, v27 offset0:56 offset1:122
	ds_write2_b32 v18, v28, v20 offset0:188 offset1:254
	s_waitcnt lgkmcnt(0)
	ds_read2_b32 v[20:21], v7 offset1:33
	s_waitcnt lgkmcnt(0)
	s_nop 1
	v_cvt_pk_bf16_f32 v20, v20, v21
	ds_read2_b32 v[22:23], v7 offset0:66 offset1:99
	v_or_b32_e32 v19, s0, v6
	s_waitcnt lgkmcnt(0)
	s_nop 1
	v_cvt_pk_bf16_f32 v21, v22, v23
	ds_read2_b32 v[22:23], v7 offset0:132 offset1:165
	v_lshl_add_u64 v[26:27], v[2:3], 0, s[6:7]
	v_lshlrev_b32_e32 v28, 12, v19
	v_mov_b32_e32 v29, v1
	s_waitcnt lgkmcnt(0)
	s_nop 1
	v_cvt_pk_bf16_f32 v22, v22, v23
	ds_read2_b32 v[24:25], v7 offset0:198 offset1:231
	s_waitcnt lgkmcnt(0)
	s_nop 1
	v_cvt_pk_bf16_f32 v23, v24, v25
	v_lshl_add_u64 v[28:29], v[26:27], 0, v[28:29]
	ds_read2_b32 v[24:25], v7 offset0:8 offset1:41
	global_store_dwordx4 v[28:29], v[20:23], off
	v_or_b32_e32 v19, s0, v8
	v_lshlrev_b32_e32 v28, 12, v19
	s_waitcnt lgkmcnt(0)
	s_nop 1
	v_cvt_pk_bf16_f32 v20, v24, v25
	ds_read2_b32 v[22:23], v7 offset0:74 offset1:107
	s_waitcnt lgkmcnt(0)
	s_nop 1
	v_cvt_pk_bf16_f32 v21, v22, v23
	ds_read2_b32 v[22:23], v7 offset0:140 offset1:173
	v_mov_b32_e32 v29, v1
	s_waitcnt lgkmcnt(0)
	s_nop 1
	v_cvt_pk_bf16_f32 v22, v22, v23
	ds_read2_b32 v[24:25], v7 offset0:206 offset1:239
	s_waitcnt lgkmcnt(0)
	s_nop 1
	v_cvt_pk_bf16_f32 v23, v24, v25
	v_lshl_add_u64 v[28:29], v[26:27], 0, v[28:29]
	ds_read2_b32 v[24:25], v7 offset0:16 offset1:49
	global_store_dwordx4 v[28:29], v[20:23], off
	v_or_b32_e32 v19, s0, v9
	v_mov_b32_e32 v29, v1
	s_waitcnt lgkmcnt(0)
	s_nop 1
	v_cvt_pk_bf16_f32 v20, v24, v25
	ds_read2_b32 v[22:23], v7 offset0:82 offset1:115
	s_waitcnt lgkmcnt(0)
	s_nop 1
	v_cvt_pk_bf16_f32 v21, v22, v23
	ds_read2_b32 v[22:23], v7 offset0:148 offset1:181
	v_lshlrev_b32_e32 v28, 12, v19
	s_waitcnt lgkmcnt(0)
	s_nop 1
	v_cvt_pk_bf16_f32 v22, v22, v23
	ds_read2_b32 v[24:25], v7 offset0:214 offset1:247
	s_waitcnt lgkmcnt(0)
	s_nop 1
	v_cvt_pk_bf16_f32 v23, v24, v25
	v_lshl_add_u64 v[28:29], v[26:27], 0, v[28:29]
	ds_read2_b32 v[24:25], v7 offset0:24 offset1:57
	global_store_dwordx4 v[28:29], v[20:23], off
	v_or_b32_e32 v19, s0, v10
	v_mov_b32_e32 v29, v1
	s_waitcnt lgkmcnt(0)
	s_nop 1
	v_cvt_pk_bf16_f32 v20, v24, v25
	ds_read2_b32 v[22:23], v7 offset0:90 offset1:123
	s_waitcnt lgkmcnt(0)
	s_nop 1
	v_cvt_pk_bf16_f32 v21, v22, v23
	ds_read2_b32 v[22:23], v7 offset0:156 offset1:189
	s_waitcnt lgkmcnt(0)
	s_nop 1
	v_cvt_pk_bf16_f32 v22, v22, v23
	ds_read2_b32 v[24:25], v7 offset0:222 offset1:255
	v_lshlrev_b32_e32 v28, 12, v19
	s_waitcnt lgkmcnt(0)
	s_nop 1
	v_cvt_pk_bf16_f32 v23, v24, v25
	v_lshl_add_u64 v[24:25], v[26:27], 0, v[28:29]
	global_store_dwordx4 v[24:25], v[20:23], off
	s_waitcnt lgkmcnt(0)

.LBB0_237:
	s_andn2_b64 vcc, exec, s[0:1]
	s_cbranch_vccnz .LBB0_239
	v_readlane_b32 s0, v255, 10
	v_readlane_b32 s1, v255, 11
	v_mov_b32_e32 v23, v1
	s_nop 0
	v_mov_b64_e32 v[20:21], s[0:1]
	flat_load_dwordx2 v[20:21], v[20:21] offset:104
	s_waitcnt vmcnt(0)
	s_add_i32 s1, s4, 0xf800
	s_and_b32 s1, s1, 0xffc0
	v_or_b32_e32 v19, s1, v4
	s_and_b32 s0, s14, 0x7e0
	v_lshlrev_b32_e32 v22, 13, v19
	s_lshl_b32 s6, s0, 2
	s_bitset1_b32 s0, 11
	s_waitcnt lgkmcnt(0)
	v_readfirstlane_b32 s11, v21
	v_readfirstlane_b32 s10, v20
	s_nop 1
	v_lshl_add_u64 v[20:21], s[10:11], 0, v[22:23]
	v_lshl_add_u64 v[20:21], v[20:21], 0, s[6:7]
	v_lshl_add_u64 v[20:21], v[20:21], 0, v[0:1]
	v_add_co_u32_e32 v22, vcc, s28, v20
	s_lshl_b32 s6, s1, 1
	s_nop 0
	v_addc_co_u32_e32 v23, vcc, 0, v21, vcc
	v_add_co_u32_e32 v24, vcc, s37, v20
	s_nop 1
	v_addc_co_u32_e32 v25, vcc, 0, v21, vcc
	v_add_co_u32_e32 v26, vcc, s43, v20
	s_nop 1
	v_addc_co_u32_e32 v27, vcc, 0, v21, vcc
	v_add_co_u32_e32 v28, vcc, s53, v20
	s_nop 1
	v_addc_co_u32_e32 v29, vcc, 0, v21, vcc
	v_add_co_u32_e32 v30, vcc, s54, v20
	s_nop 1
	v_addc_co_u32_e32 v31, vcc, 0, v21, vcc
	v_add_co_u32_e32 v32, vcc, s55, v20
	s_nop 1
	v_addc_co_u32_e32 v33, vcc, 0, v21, vcc
	v_add_co_u32_e32 v34, vcc, s56, v20
	s_nop 1
	v_addc_co_u32_e32 v35, vcc, 0, v21, vcc
	v_add_co_u32_e32 v36, vcc, s57, v20
	s_nop 1
	v_addc_co_u32_e32 v37, vcc, 0, v21, vcc
	v_add_co_u32_e32 v38, vcc, s58, v20
	s_nop 1
	v_addc_co_u32_e32 v39, vcc, 0, v21, vcc
	v_add_co_u32_e32 v40, vcc, s59, v20
	s_nop 1
	v_addc_co_u32_e32 v41, vcc, 0, v21, vcc
	v_add_co_u32_e32 v42, vcc, s60, v20
	s_nop 1
	v_addc_co_u32_e32 v43, vcc, 0, v21, vcc
	v_add_co_u32_e32 v44, vcc, s61, v20
	s_nop 1
	v_addc_co_u32_e32 v45, vcc, 0, v21, vcc
	v_add_co_u32_e32 v46, vcc, s62, v20
	s_nop 1
	v_addc_co_u32_e32 v47, vcc, 0, v21, vcc
	v_add_co_u32_e32 v48, vcc, s63, v20
	s_nop 1
	v_addc_co_u32_e32 v49, vcc, 0, v21, vcc
	v_add_co_u32_e32 v50, vcc, s64, v20
	s_nop 1
	v_addc_co_u32_e32 v51, vcc, 0, v21, vcc
	flat_load_dword v19, v[20:21] nt
	flat_load_dword v52, v[22:23] nt
	flat_load_dword v53, v[24:25] nt
	flat_load_dword v54, v[26:27] nt
	flat_load_dword v55, v[28:29] nt
	flat_load_dword v56, v[30:31] nt
	flat_load_dword v57, v[32:33] nt
	flat_load_dword v58, v[34:35] nt
	flat_load_dword v59, v[36:37] nt
	s_nop 0
	flat_load_dword v38, v[38:39] nt
	s_nop 0
	flat_load_dword v39, v[40:41] nt
	s_nop 0
	flat_load_dword v40, v[42:43] nt
	flat_load_dword v41, v[44:45] nt
	s_nop 0
	flat_load_dword v42, v[46:47] nt
	flat_load_dword v43, v[48:49] nt
	flat_load_dword v44, v[50:51] nt
	v_add_co_u32_e32 v22, vcc, s65, v20
	s_nop 1
	v_addc_co_u32_e32 v23, vcc, 0, v21, vcc
	v_add_co_u32_e32 v24, vcc, s66, v20
	s_nop 1
	v_addc_co_u32_e32 v25, vcc, 0, v21, vcc
	v_add_co_u32_e32 v26, vcc, s67, v20
	s_nop 1
	v_addc_co_u32_e32 v27, vcc, 0, v21, vcc
	v_add_co_u32_e32 v28, vcc, s68, v20
	s_nop 1
	v_addc_co_u32_e32 v29, vcc, 0, v21, vcc
	v_add_co_u32_e32 v30, vcc, s69, v20
	s_nop 1
	v_addc_co_u32_e32 v31, vcc, 0, v21, vcc
	v_add_co_u32_e32 v32, vcc, s70, v20
	s_nop 1
	v_addc_co_u32_e32 v33, vcc, 0, v21, vcc
	v_add_co_u32_e32 v34, vcc, s71, v20
	s_nop 1
	v_addc_co_u32_e32 v35, vcc, 0, v21, vcc
	v_add_co_u32_e32 v36, vcc, s72, v20
	s_nop 1
	v_addc_co_u32_e32 v37, vcc, 0, v21, vcc
	flat_load_dword v45, v[22:23] nt
	flat_load_dword v46, v[24:25] nt
	flat_load_dword v47, v[26:27] nt
	flat_load_dword v48, v[28:29] nt
	flat_load_dword v49, v[30:31] nt
	flat_load_dword v50, v[32:33] nt
	flat_load_dword v51, v[34:35] nt
	s_nop 0
	flat_load_dword v36, v[36:37] nt
	v_add_co_u32_e32 v22, vcc, s73, v20
	s_nop 1
	v_addc_co_u32_e32 v23, vcc, 0, v21, vcc
	v_add_co_u32_e32 v24, vcc, s74, v20
	s_nop 1
	v_addc_co_u32_e32 v25, vcc, 0, v21, vcc
	v_add_co_u32_e32 v26, vcc, s75, v20
	s_nop 1
	v_addc_co_u32_e32 v27, vcc, 0, v21, vcc
	v_add_co_u32_e32 v28, vcc, s76, v20
	s_nop 1
	v_addc_co_u32_e32 v29, vcc, 0, v21, vcc
	v_add_co_u32_e32 v30, vcc, s77, v20
	s_nop 1
	v_addc_co_u32_e32 v31, vcc, 0, v21, vcc
	v_add_co_u32_e32 v32, vcc, s78, v20
	s_nop 1
	v_addc_co_u32_e32 v33, vcc, 0, v21, vcc
	v_add_co_u32_e32 v34, vcc, s79, v20
	s_nop 1
	v_addc_co_u32_e32 v35, vcc, 0, v21, vcc
	v_add_co_u32_e32 v20, vcc, s80, v20
	s_nop 1
	v_addc_co_u32_e32 v21, vcc, 0, v21, vcc
	flat_load_dword v22, v[22:23] nt
	s_nop 0
	flat_load_dword v23, v[24:25] nt
	s_nop 0
	flat_load_dword v24, v[26:27] nt
	flat_load_dword v25, v[28:29] nt
	s_nop 0
	flat_load_dword v26, v[30:31] nt
	flat_load_dword v27, v[32:33] nt
	flat_load_dword v28, v[34:35] nt
	s_nop 0
	flat_load_dword v20, v[20:21] nt
	s_waitcnt vmcnt(0) lgkmcnt(0)
	ds_write2_b32 v5, v19, v52 offset1:66
	ds_write2_b32 v5, v53, v54 offset0:132 offset1:198
	ds_write2_b32 v12, v55, v56 offset0:8 offset1:74
	ds_write2_b32 v12, v57, v58 offset0:140 offset1:206
	ds_write2_b32 v13, v59, v38 offset0:16 offset1:82
	ds_write2_b32 v13, v39, v40 offset0:148 offset1:214
	ds_write2_b32 v14, v41, v42 offset0:24 offset1:90
	ds_write2_b32 v14, v43, v44 offset0:156 offset1:222
	ds_write2_b32 v15, v45, v46 offset0:32 offset1:98
	ds_write2_b32 v15, v47, v48 offset0:164 offset1:230
	ds_write2_b32 v16, v49, v50 offset0:40 offset1:106
	ds_write2_b32 v16, v51, v36 offset0:172 offset1:238
	ds_write2_b32 v17, v22, v23 offset0:48 offset1:114
	ds_write2_b32 v17, v24, v25 offset0:180 offset1:246
	ds_write2_b32 v18, v26, v27 offset0:56 offset1:122
	ds_write2_b32 v18, v28, v20 offset0:188 offset1:254
	s_waitcnt lgkmcnt(0)
	ds_read2_b32 v[20:21], v7 offset1:33
	s_waitcnt lgkmcnt(0)
	s_nop 1
	v_cvt_pk_bf16_f32 v20, v20, v21
	ds_read2_b32 v[22:23], v7 offset0:66 offset1:99
	v_or_b32_e32 v19, s0, v6
	s_waitcnt lgkmcnt(0)
	s_nop 1
	v_cvt_pk_bf16_f32 v21, v22, v23
	ds_read2_b32 v[22:23], v7 offset0:132 offset1:165
	v_lshl_add_u64 v[26:27], v[2:3], 0, s[6:7]
	v_lshlrev_b32_e32 v28, 12, v19
	v_mov_b32_e32 v29, v1
	s_waitcnt lgkmcnt(0)
	s_nop 1
	v_cvt_pk_bf16_f32 v22, v22, v23
	ds_read2_b32 v[24:25], v7 offset0:198 offset1:231
	s_waitcnt lgkmcnt(0)
	s_nop 1
	v_cvt_pk_bf16_f32 v23, v24, v25
	v_lshl_add_u64 v[28:29], v[26:27], 0, v[28:29]
	ds_read2_b32 v[24:25], v7 offset0:8 offset1:41
	global_store_dwordx4 v[28:29], v[20:23], off
	v_or_b32_e32 v19, s0, v8
	v_lshlrev_b32_e32 v28, 12, v19
	s_waitcnt lgkmcnt(0)
	s_nop 1
	v_cvt_pk_bf16_f32 v20, v24, v25
	ds_read2_b32 v[22:23], v7 offset0:74 offset1:107
	s_waitcnt lgkmcnt(0)
	s_nop 1
	v_cvt_pk_bf16_f32 v21, v22, v23
	ds_read2_b32 v[22:23], v7 offset0:140 offset1:173
	v_mov_b32_e32 v29, v1
	s_waitcnt lgkmcnt(0)
	s_nop 1
	v_cvt_pk_bf16_f32 v22, v22, v23
	ds_read2_b32 v[24:25], v7 offset0:206 offset1:239
	s_waitcnt lgkmcnt(0)
	s_nop 1
	v_cvt_pk_bf16_f32 v23, v24, v25
	v_lshl_add_u64 v[28:29], v[26:27], 0, v[28:29]
	ds_read2_b32 v[24:25], v7 offset0:16 offset1:49
	global_store_dwordx4 v[28:29], v[20:23], off
	v_or_b32_e32 v19, s0, v9
	v_mov_b32_e32 v29, v1
	s_waitcnt lgkmcnt(0)
	s_nop 1
	v_cvt_pk_bf16_f32 v20, v24, v25
	ds_read2_b32 v[22:23], v7 offset0:82 offset1:115
	s_waitcnt lgkmcnt(0)
	s_nop 1
	v_cvt_pk_bf16_f32 v21, v22, v23
	ds_read2_b32 v[22:23], v7 offset0:148 offset1:181
	v_lshlrev_b32_e32 v28, 12, v19
	s_waitcnt lgkmcnt(0)
	s_nop 1
	v_cvt_pk_bf16_f32 v22, v22, v23
	ds_read2_b32 v[24:25], v7 offset0:214 offset1:247
	s_waitcnt lgkmcnt(0)
	s_nop 1
	v_cvt_pk_bf16_f32 v23, v24, v25
	v_lshl_add_u64 v[28:29], v[26:27], 0, v[28:29]
	ds_read2_b32 v[24:25], v7 offset0:24 offset1:57
	global_store_dwordx4 v[28:29], v[20:23], off
	v_or_b32_e32 v19, s0, v10
	v_mov_b32_e32 v29, v1
	s_waitcnt lgkmcnt(0)
	s_nop 1
	v_cvt_pk_bf16_f32 v20, v24, v25
	ds_read2_b32 v[22:23], v7 offset0:90 offset1:123
	s_waitcnt lgkmcnt(0)
	s_nop 1
	v_cvt_pk_bf16_f32 v21, v22, v23
	ds_read2_b32 v[22:23], v7 offset0:156 offset1:189
	s_waitcnt lgkmcnt(0)
	s_nop 1
	v_cvt_pk_bf16_f32 v22, v22, v23
	ds_read2_b32 v[24:25], v7 offset0:222 offset1:255
	v_lshlrev_b32_e32 v28, 12, v19
	s_waitcnt lgkmcnt(0)
	s_nop 1
	v_cvt_pk_bf16_f32 v23, v24, v25
	v_lshl_add_u64 v[24:25], v[26:27], 0, v[28:29]
	global_store_dwordx4 v[24:25], v[20:23], off
	s_waitcnt lgkmcnt(0)

.LBB0_240:
	s_andn2_b64 vcc, exec, s[0:1]
	s_cbranch_vccnz .LBB0_213
	v_readlane_b32 s0, v255, 10
	v_readlane_b32 s1, v255, 11
	s_nop 1
	v_mov_b64_e32 v[20:21], s[0:1]
	flat_load_dwordx2 v[20:21], v[20:21] offset:96
	s_waitcnt vmcnt(0)
	s_ashr_i32 s0, s4, 31
	s_lshr_b32 s0, s0, 26
	s_add_i32 s0, s4, s0
	s_and_b32 s12, s0, 0xffffffc0
	s_lshl_b32 s1, s0, 5
	v_or_b32_e32 v22, s12, v4
	s_and_b32 s0, s1, 0xfffff800
	v_ashrrev_i32_e32 v23, 31, v22
	s_sub_i32 s10, s14, s0
	v_lshlrev_b64 v[22:23], 13, v[22:23]
	s_ashr_i32 s11, s10, 31
	s_ashr_i32 s13, s12, 31
	s_waitcnt lgkmcnt(0)
	v_readfirstlane_b32 s1, v21
	v_readfirstlane_b32 s0, v20
	s_nop 1
	v_lshl_add_u64 v[20:21], s[0:1], 0, v[22:23]
	v_lshl_add_u64 v[20:21], s[10:11], 2, v[20:21]
	v_lshl_add_u64 v[20:21], v[20:21], 0, v[0:1]
	v_add_co_u32_e32 v22, vcc, s28, v20
	s_nop 1
	v_addc_co_u32_e32 v23, vcc, 0, v21, vcc
	v_add_co_u32_e32 v24, vcc, s37, v20
	s_nop 1
	v_addc_co_u32_e32 v25, vcc, 0, v21, vcc
	v_add_co_u32_e32 v26, vcc, s43, v20
	s_nop 1
	v_addc_co_u32_e32 v27, vcc, 0, v21, vcc
	v_add_co_u32_e32 v28, vcc, s53, v20
	s_nop 1
	v_addc_co_u32_e32 v29, vcc, 0, v21, vcc
	v_add_co_u32_e32 v30, vcc, s54, v20
	s_nop 1
	v_addc_co_u32_e32 v31, vcc, 0, v21, vcc
	v_add_co_u32_e32 v32, vcc, s55, v20
	s_nop 1
	v_addc_co_u32_e32 v33, vcc, 0, v21, vcc
	v_add_co_u32_e32 v34, vcc, s56, v20
	s_nop 1
	v_addc_co_u32_e32 v35, vcc, 0, v21, vcc
	v_add_co_u32_e32 v36, vcc, s57, v20
	s_nop 1
	v_addc_co_u32_e32 v37, vcc, 0, v21, vcc
	v_add_co_u32_e32 v38, vcc, s58, v20
	s_nop 1
	v_addc_co_u32_e32 v39, vcc, 0, v21, vcc
	v_add_co_u32_e32 v40, vcc, s59, v20
	s_nop 1
	v_addc_co_u32_e32 v41, vcc, 0, v21, vcc
	v_add_co_u32_e32 v42, vcc, s60, v20
	s_nop 1
	v_addc_co_u32_e32 v43, vcc, 0, v21, vcc
	v_add_co_u32_e32 v44, vcc, s61, v20
	s_nop 1
	v_addc_co_u32_e32 v45, vcc, 0, v21, vcc
	v_add_co_u32_e32 v46, vcc, s62, v20
	s_nop 1
	v_addc_co_u32_e32 v47, vcc, 0, v21, vcc
	v_add_co_u32_e32 v48, vcc, s63, v20
	s_nop 1
	v_addc_co_u32_e32 v49, vcc, 0, v21, vcc
	v_add_co_u32_e32 v50, vcc, s64, v20
	s_nop 1
	v_addc_co_u32_e32 v51, vcc, 0, v21, vcc
	flat_load_dword v19, v[20:21] nt
	flat_load_dword v52, v[22:23] nt
	flat_load_dword v53, v[24:25] nt
	flat_load_dword v54, v[26:27] nt
	flat_load_dword v55, v[28:29] nt
	flat_load_dword v56, v[30:31] nt
	flat_load_dword v57, v[32:33] nt
	flat_load_dword v58, v[34:35] nt
	flat_load_dword v59, v[36:37] nt
	s_nop 0
	flat_load_dword v38, v[38:39] nt
	s_nop 0
	flat_load_dword v39, v[40:41] nt
	s_nop 0
	flat_load_dword v40, v[42:43] nt
	flat_load_dword v41, v[44:45] nt
	s_nop 0
	flat_load_dword v42, v[46:47] nt
	flat_load_dword v43, v[48:49] nt
	flat_load_dword v44, v[50:51] nt
	v_add_co_u32_e32 v22, vcc, s65, v20
	s_nop 1
	v_addc_co_u32_e32 v23, vcc, 0, v21, vcc
	v_add_co_u32_e32 v24, vcc, s66, v20
	s_nop 1
	v_addc_co_u32_e32 v25, vcc, 0, v21, vcc
	v_add_co_u32_e32 v26, vcc, s67, v20
	s_nop 1
	v_addc_co_u32_e32 v27, vcc, 0, v21, vcc
	v_add_co_u32_e32 v28, vcc, s68, v20
	s_nop 1
	v_addc_co_u32_e32 v29, vcc, 0, v21, vcc
	v_add_co_u32_e32 v30, vcc, s69, v20
	s_nop 1
	v_addc_co_u32_e32 v31, vcc, 0, v21, vcc
	v_add_co_u32_e32 v32, vcc, s70, v20
	s_nop 1
	v_addc_co_u32_e32 v33, vcc, 0, v21, vcc
	v_add_co_u32_e32 v34, vcc, s71, v20
	s_nop 1
	v_addc_co_u32_e32 v35, vcc, 0, v21, vcc
	v_add_co_u32_e32 v36, vcc, s72, v20
	s_nop 1
	v_addc_co_u32_e32 v37, vcc, 0, v21, vcc
	flat_load_dword v45, v[22:23] nt
	flat_load_dword v46, v[24:25] nt
	flat_load_dword v47, v[26:27] nt
	flat_load_dword v48, v[28:29] nt
	flat_load_dword v49, v[30:31] nt
	flat_load_dword v50, v[32:33] nt
	flat_load_dword v51, v[34:35] nt
	s_nop 0
	flat_load_dword v36, v[36:37] nt
	v_add_co_u32_e32 v22, vcc, s73, v20
	s_nop 1
	v_addc_co_u32_e32 v23, vcc, 0, v21, vcc
	v_add_co_u32_e32 v24, vcc, s74, v20
	s_nop 1
	v_addc_co_u32_e32 v25, vcc, 0, v21, vcc
	v_add_co_u32_e32 v26, vcc, s75, v20
	s_nop 1
	v_addc_co_u32_e32 v27, vcc, 0, v21, vcc
	v_add_co_u32_e32 v28, vcc, s76, v20
	s_nop 1
	v_addc_co_u32_e32 v29, vcc, 0, v21, vcc
	v_add_co_u32_e32 v30, vcc, s77, v20
	s_nop 1
	v_addc_co_u32_e32 v31, vcc, 0, v21, vcc
	v_add_co_u32_e32 v32, vcc, s78, v20
	s_nop 1
	v_addc_co_u32_e32 v33, vcc, 0, v21, vcc
	v_add_co_u32_e32 v34, vcc, s79, v20
	s_nop 1
	v_addc_co_u32_e32 v35, vcc, 0, v21, vcc
	v_add_co_u32_e32 v20, vcc, s80, v20
	s_nop 1
	v_addc_co_u32_e32 v21, vcc, 0, v21, vcc
	flat_load_dword v22, v[22:23] nt
	s_nop 0
	flat_load_dword v23, v[24:25] nt
	s_nop 0
	flat_load_dword v24, v[26:27] nt
	flat_load_dword v25, v[28:29] nt
	s_nop 0
	flat_load_dword v26, v[30:31] nt
	flat_load_dword v27, v[32:33] nt
	flat_load_dword v28, v[34:35] nt
	s_nop 0
	flat_load_dword v20, v[20:21] nt
	s_waitcnt vmcnt(0) lgkmcnt(0)
	ds_write2_b32 v5, v19, v52 offset1:66
	ds_write2_b32 v5, v53, v54 offset0:132 offset1:198
	ds_write2_b32 v12, v55, v56 offset0:8 offset1:74
	ds_write2_b32 v12, v57, v58 offset0:140 offset1:206
	ds_write2_b32 v13, v59, v38 offset0:16 offset1:82
	ds_write2_b32 v13, v39, v40 offset0:148 offset1:214
	ds_write2_b32 v14, v41, v42 offset0:24 offset1:90
	ds_write2_b32 v14, v43, v44 offset0:156 offset1:222
	ds_write2_b32 v15, v45, v46 offset0:32 offset1:98
	ds_write2_b32 v15, v47, v48 offset0:164 offset1:230
	ds_write2_b32 v16, v49, v50 offset0:40 offset1:106
	ds_write2_b32 v16, v51, v36 offset0:172 offset1:238
	ds_write2_b32 v17, v22, v23 offset0:48 offset1:114
	ds_write2_b32 v17, v24, v25 offset0:180 offset1:246
	ds_write2_b32 v18, v26, v27 offset0:56 offset1:122
	ds_write2_b32 v18, v28, v20 offset0:188 offset1:254
	s_waitcnt lgkmcnt(0)
	ds_read2_b32 v[20:21], v7 offset1:33
	s_waitcnt lgkmcnt(0)
	s_nop 1
	v_cvt_pk_bf16_f32 v20, v20, v21
	ds_read2_b32 v[22:23], v7 offset0:66 offset1:99
	s_waitcnt lgkmcnt(0)
	s_nop 1
	v_cvt_pk_bf16_f32 v21, v22, v23
	ds_read2_b32 v[22:23], v7 offset0:132 offset1:165
	s_waitcnt lgkmcnt(0)
	s_nop 1
	v_cvt_pk_bf16_f32 v22, v22, v23
	ds_read2_b32 v[24:25], v7 offset0:198 offset1:231
	s_waitcnt lgkmcnt(0)
	s_nop 1
	v_cvt_pk_bf16_f32 v23, v24, v25
	v_add_u32_e32 v24, s10, v6
	v_ashrrev_i32_e32 v25, 31, v24
	v_lshl_add_u64 v[26:27], s[12:13], 1, v[2:3]
	v_lshlrev_b64 v[30:31], 12, v[24:25]
	v_lshl_add_u64 v[30:31], v[26:27], 0, v[30:31]
	ds_read2_b32 v[28:29], v7 offset0:8 offset1:41
	global_store_dwordx4 v[30:31], v[20:23], off
	s_waitcnt lgkmcnt(0)
	s_nop 0
	s_nop 1
	v_cvt_pk_bf16_f32 v20, v28, v29
	ds_read2_b32 v[22:23], v7 offset0:74 offset1:107
	s_waitcnt lgkmcnt(0)
	s_nop 1
	v_cvt_pk_bf16_f32 v21, v22, v23
	ds_read2_b32 v[22:23], v7 offset0:140 offset1:173
	s_waitcnt lgkmcnt(0)
	s_nop 1
	v_cvt_pk_bf16_f32 v22, v22, v23
	ds_read2_b32 v[28:29], v7 offset0:206 offset1:239
	s_waitcnt lgkmcnt(0)
	s_nop 1
	v_cvt_pk_bf16_f32 v23, v28, v29
	v_add_u32_e32 v28, 8, v24
	v_ashrrev_i32_e32 v29, 31, v28
	v_lshlrev_b64 v[28:29], 12, v[28:29]
	ds_read2_b32 v[30:31], v7 offset0:16 offset1:49
	v_lshl_add_u64 v[28:29], v[26:27], 0, v[28:29]
	global_store_dwordx4 v[28:29], v[20:23], off
	s_waitcnt lgkmcnt(0)
	s_nop 0
	s_nop 1
	v_cvt_pk_bf16_f32 v20, v30, v31
	v_add_u32_e32 v30, 16, v24
	ds_read2_b32 v[22:23], v7 offset0:82 offset1:115
	v_ashrrev_i32_e32 v31, 31, v30
	s_waitcnt lgkmcnt(0)
	s_nop 1
	v_cvt_pk_bf16_f32 v21, v22, v23
	ds_read2_b32 v[22:23], v7 offset0:148 offset1:181
	v_lshlrev_b64 v[30:31], 12, v[30:31]
	v_add_u32_e32 v24, 24, v24
	s_waitcnt lgkmcnt(0)
	s_nop 1
	v_cvt_pk_bf16_f32 v22, v22, v23
	ds_read2_b32 v[28:29], v7 offset0:214 offset1:247
	s_waitcnt lgkmcnt(0)
	s_nop 1
	v_cvt_pk_bf16_f32 v23, v28, v29
	v_lshl_add_u64 v[30:31], v[26:27], 0, v[30:31]
	v_ashrrev_i32_e32 v25, 31, v24
	ds_read2_b32 v[28:29], v7 offset0:24 offset1:57
	global_store_dwordx4 v[30:31], v[20:23], off
	v_lshlrev_b64 v[24:25], 12, v[24:25]
	v_lshl_add_u64 v[24:25], v[26:27], 0, v[24:25]
	s_waitcnt lgkmcnt(0)
	s_nop 1
	v_cvt_pk_bf16_f32 v20, v28, v29
	ds_read2_b32 v[22:23], v7 offset0:90 offset1:123
	s_waitcnt lgkmcnt(0)
	s_nop 1
	v_cvt_pk_bf16_f32 v21, v22, v23
	ds_read2_b32 v[22:23], v7 offset0:156 offset1:189
	s_waitcnt lgkmcnt(0)
	s_nop 1
	v_cvt_pk_bf16_f32 v22, v22, v23
	ds_read2_b32 v[28:29], v7 offset0:222 offset1:255
	s_waitcnt lgkmcnt(0)
	s_nop 1
	v_cvt_pk_bf16_f32 v23, v28, v29
	global_store_dwordx4 v[24:25], v[20:23], off
	s_waitcnt lgkmcnt(0)
	s_branch .LBB0_213

.LBB0_442:
	s_add_u32 s4, s26, 0x100000
	s_addc_u32 s5, s27, 0
	v_writelane_b32 v255, s4, 16
	s_nop 1
	v_writelane_b32 v255, s5, 17
	s_add_u32 s4, s26, 0x500000
	s_addc_u32 s5, s27, 0
	v_writelane_b32 v255, s4, 18
	s_andn2_b64 vcc, exec, s[0:1]
	s_nop 0
	v_writelane_b32 v255, s5, 19
	s_cbranch_vccnz .LBB0_474
	v_mov_b64_e32 v[0:1], s[58:59]
	flat_load_dwordx2 v[2:3], v[0:1] offset:264
	flat_load_dwordx2 v[4:5], v[0:1] offset:272
	flat_load_dwordx2 v[6:7], v[0:1] offset:280
	flat_load_dwordx2 v[8:9], v[0:1] offset:288
	flat_load_dwordx2 v[10:11], v[0:1] offset:296
	flat_load_dwordx2 v[12:13], v[0:1] offset:304
	flat_load_dwordx2 v[14:15], v[0:1] offset:312
	s_waitcnt vmcnt(0)
	s_movk_i32 s0, 0x840
	v_ashrrev_i32_e32 v129, 31, v128
	v_cmp_gt_i32_e32 vcc, s0, v128
	s_waitcnt lgkmcnt(0)
	v_readfirstlane_b32 s43, v3
	v_readfirstlane_b32 s42, v2
	v_readfirstlane_b32 s5, v5
	v_readfirstlane_b32 s4, v4
	v_readfirstlane_b32 s7, v7
	v_readfirstlane_b32 s6, v6
	v_readfirstlane_b32 s13, v9
	v_readfirstlane_b32 s12, v8
	v_readfirstlane_b32 s9, v11
	v_readfirstlane_b32 s8, v10
	v_readfirstlane_b32 s37, v13
	v_readfirstlane_b32 s36, v12
	v_readfirstlane_b32 s1, v15
	v_readfirstlane_b32 s0, v14
	v_lshl_add_u32 v2, v128, 2, 0
	s_and_saveexec_b64 s[10:11], vcc
	s_cbranch_execz .LBB0_446
	v_add_u32_e32 v3, 0x2000, v2
	v_add_u32_e32 v4, 0xfffffe00, v128
	v_lshl_add_u64 v[0:1], v[128:129], 2, s[42:43]
	s_mov_b64 s[42:43], 0
	s_mov_b64 s[44:45], 0x800
	s_movk_i32 s15, 0x63f

.LBB0_470:
	v_mov_b64_e32 v[2:3], s[58:59]
	flat_load_dwordx2 v[4:5], v[2:3] offset:320
	s_waitcnt vmcnt(0)
	s_ashr_i32 s41, s40, 31
	s_lshl_b64 s[4:5], s[40:41], 9
	s_mov_b64 s[0:1], 0x40000
	v_lshl_add_u64 v[2:3], s[4:5], 0, v[128:129]
	v_cmp_gt_u64_e32 vcc, s[0:1], v[2:3]
	s_waitcnt lgkmcnt(0)
	v_readfirstlane_b32 s7, v5
	v_readfirstlane_b32 s6, v4
	s_and_saveexec_b64 s[0:1], vcc
	s_cbranch_execz .LBB0_473
	v_lshlrev_b32_e32 v4, 14, v14
	v_mov_b32_e32 v5, 0
	v_lshl_add_u64 v[6:7], s[6:7], 0, v[4:5]
	v_readlane_b32 s6, v255, 18
	s_ashr_i32 s15, s14, 31
	v_mov_b32_e32 v1, v5
	v_readlane_b32 s7, v255, 19
	s_lshl_b64 s[4:5], s[14:15], 9
	s_movk_i32 s10, 0x7fff
	v_lshl_add_u64 v[0:1], s[6:7], 0, v[0:1]
	s_mov_b64 s[6:7], 0
	s_mov_b64 s[8:9], 0x3ffff

.Lprio_skip2:
	s_add_u32 s60, s26, 0x1c900000
	v_mov_b64_e32 v[0:1], s[58:59]
	flat_load_dwordx2 v[2:3], v[0:1] offset:128
	flat_load_dwordx2 v[4:5], v[0:1] offset:152
	s_waitcnt vmcnt(0)
	s_addc_u32 s61, s27, 0
	s_add_u32 s52, s26, 0x24d00000
	s_addc_u32 s53, s27, 0
	s_add_u32 s56, s26, 0x28f00000
	v_mov_b32_e32 v8, v254
	s_addc_u32 s57, s27, 0
	s_cmpk_lt_i32 s2, 0x528
	v_readfirstlane_b32 s4, v8
	s_waitcnt lgkmcnt(0)
	v_readfirstlane_b32 s41, v3
	v_readfirstlane_b32 s40, v2
	v_readfirstlane_b32 s43, v5
	v_readfirstlane_b32 s42, v4
	s_cbranch_scc0 .LBB0_547
	v_lshlrev_b32_e32 v0, 4, v8
	v_add_u32_e32 v1, 0x2000, v0
	v_ashrrev_i32_e32 v2, 31, v1
	v_lshrrev_b32_e32 v2, 22, v2
	v_add_u32_e32 v2, v1, v2
	v_ashrrev_i32_e32 v2, 10, v2
	v_mul_i32_i24_e32 v3, 0x400, v2
	v_sub_u32_e32 v1, v1, v3
	v_lshrrev_b32_e32 v3, 4, v1
	v_bitop3_b32 v1, v3, v1, 32 bitop3:0x6c
	v_ashrrev_i32_e32 v3, 31, v1
	v_lshrrev_b32_e32 v3, 26, v3
	v_add_u32_e32 v3, v1, v3
	v_lshlrev_b32_e32 v5, 3, v2
	v_ashrrev_i32_e32 v4, 6, v3
	v_and_b32_e32 v5, -16, v5
	v_and_b32_e32 v3, 0xc0, v3
	v_add_u32_e32 v5, v4, v5
	v_sub_u32_e32 v1, v1, v3
	v_mov_b32_e32 v3, 1
	v_and_b32_e32 v4, 3, v4
	s_mov_b32 s6, 0x7fffe0
	v_lshrrev_b32_e32 v6, 2, v5
	v_lshlrev_b32_e32 v7, 1, v5
	v_lshlrev_b32_e32 v2, 5, v2
	v_ashrrev_i16_sdwa v1, v3, sext(v1) dst_sel:DWORD dst_unused:UNUSED_PAD src0_sel:DWORD src1_sel:BYTE_0
	v_and_or_b32 v4, v5, s6, v4
	v_and_b32_e32 v6, 4, v6
	v_and_b32_e32 v7, 24, v7
	v_and_b32_e32 v2, 32, v2
	v_bfe_i32 v1, v1, 0, 16
	v_or3_b32 v4, v4, v6, v7
	v_add_lshl_u32 v1, v2, v1, 1
	v_lshl_add_u32 v136, v4, 9, v1
	v_lshl_add_u32 v138, v5, 9, v1
	v_bfe_i32 v1, v8, 27, 1
	v_lshrrev_b32_e32 v1, 22, v1
	v_add_u32_e32 v1, v0, v1
	v_and_b32_e32 v1, 0xfffffc00, v1
	v_sub_u32_e32 v0, v0, v1
	v_ashrrev_i32_e32 v2, 31, v8
	v_lshrrev_b32_e32 v1, 4, v0
	v_lshrrev_b32_e32 v2, 26, v2
	v_bitop3_b32 v1, v1, v0, 32 bitop3:0x6c
	v_ashrrev_i32_e32 v0, 31, v0
	v_add_u32_e32 v2, v8, v2
	v_lshrrev_b32_e32 v0, 26, v0
	v_ashrrev_i32_e32 v2, 6, v2
	v_add_u32_e32 v0, v1, v0
	v_lshlrev_b32_e32 v4, 3, v2
	v_ashrrev_i32_e32 v0, 6, v0
	v_and_b32_e32 v4, -16, v4
	v_add_u32_e32 v4, v0, v4
	v_and_b32_e32 v5, 3, v0
	v_and_or_b32 v5, v4, s6, v5
	s_lshr_b32 s6, s3, 29
	s_add_i32 s6, s2, s6
	s_ashr_i32 s1, s4, 6
	s_ashr_i32 s7, s6, 3
	s_and_b32 s6, s6, -8
	s_ashr_i32 s0, s4, 8
	s_lshl_b32 s5, s1, 10
	s_sub_i32 s6, s2, s6
	s_cmp_lt_i32 s6, 0
	s_movk_i32 s28, 0xa6
	s_cselect_b32 s8, s28, 0xa5
	s_mul_i32 s6, s6, s8
	s_add_i32 s6, s6, s7
	s_mul_hi_i32 s7, s6, 0x66666667
	s_lshr_b32 s8, s7, 31
	s_ashr_i32 s7, s7, 7
	v_mul_i32_i24_e32 v0, 64, v0
	s_add_i32 s7, s7, s8
	v_sub_u32_e32 v0, v1, v0
	s_lshl_b32 s8, s7, 3
	v_lshlrev_b32_e32 v2, 5, v2
	v_ashrrev_i16_sdwa v0, v3, sext(v0) dst_sel:DWORD dst_unused:UNUSED_PAD src0_sel:DWORD src1_sel:BYTE_0
	s_sub_i32 s9, 33, s8
	s_mulk_i32 s7, 0x140
	v_and_b32_e32 v2, 32, v2
	v_bfe_i32 v0, v0, 0, 16
	s_min_u32 s9, s9, 8
	s_sub_i32 s10, s6, s7
	v_add_lshl_u32 v0, v2, v0, 1
	s_sext_i32_i16 s6, s10
	v_cvt_f32_ubyte0_e32 v2, s9
	v_cvt_f32_i32_e32 v1, s6
	v_rcp_iflag_f32_e32 v3, v2
	v_lshrrev_b32_e32 v6, 2, v4
	v_lshlrev_b32_e32 v7, 1, v4
	v_and_b32_e32 v6, 4, v6
	v_and_b32_e32 v7, 24, v7
	v_or3_b32 v5, v5, v6, v7
	v_lshl_add_u32 v140, v5, 9, v0
	v_lshl_add_u32 v142, v4, 9, v0
	v_mul_f32_e32 v0, v1, v3
	v_trunc_f32_e32 v0, v0
	v_fma_f32 v1, -v0, v2, v1
	v_cvt_i32_f32_e32 v0, v0
	s_ashr_i32 s6, s6, 30
	s_or_b32 s11, s6, 1
	v_cmp_ge_f32_e64 s[6:7], |v1|, v2
	s_and_b64 s[6:7], s[6:7], exec
	s_cselect_b32 s6, s11, 0
	v_readfirstlane_b32 s7, v0
	s_add_i32 s6, s7, s6
	s_mul_i32 s7, s6, s9
	s_sub_i32 s7, s10, s7
	s_sext_i32_i16 s7, s7
	s_add_i32 s10, s8, s7
	s_and_b32 s7, s6, 0xffff
	s_cmp_lt_u32 s7, 32
	s_mov_b32 s29, 0x420000
	s_sext_i32_i16 s20, s6
	s_cselect_b32 s7, s29, 0x840000
	s_cmp_gt_i32 s20, 15
	s_cselect_b32 s12, s7, 0
	s_ashr_i32 s11, s10, 31
	s_bfe_i64 s[6:7], s[6:7], 0x100000
	s_lshl_b64 s[8:9], s[10:11], 17
	s_lshl_b64 s[6:7], s[6:7], 17
	s_add_u32 s14, s18, s6
	s_addc_u32 s15, s19, s7
	s_add_i32 s36, s5, 0
	s_add_i32 m0, s36, 0x10000
	v_mov_b32_e32 v145, 0
	global_load_lds_dwordx4 v140, s[14:15]
	s_add_i32 m0, s36, 0x12000
	s_add_u32 s6, s16, s12
	s_addc_u32 s7, s17, 0
	s_add_u32 s12, s6, s8
	global_load_lds_dwordx4 v136, s[14:15]
	s_addc_u32 s13, s7, s9
	s_mov_b32 m0, s36
	s_add_i32 s37, s36, 0x2000
	global_load_lds_dwordx4 v142, s[12:13]
	s_mov_b32 m0, s37
	s_add_u32 s6, s14, 0x10000
	global_load_lds_dwordx4 v138, s[12:13]
	s_addc_u32 s7, s15, 0
	s_add_i32 m0, s36, 0x14000
	v_mov_b32_e32 v141, v145
	global_load_lds_dwordx4 v140, s[6:7]
	s_add_i32 m0, s36, 0x16000
	v_mov_b32_e32 v137, v145
	global_load_lds_dwordx4 v136, s[6:7]
	s_add_u32 s6, s12, 0x10000
	s_addc_u32 s7, s13, 0
	s_add_i32 s50, s36, 0x4000
	s_mov_b32 m0, s50
	s_add_i32 s51, s36, 0x6000
	global_load_lds_dwordx4 v142, s[6:7]
	s_mov_b32 m0, s51
	v_mov_b32_e32 v143, v145
	global_load_lds_dwordx4 v138, s[6:7]
	v_mov_b32_e32 v139, v145
	v_lshl_add_u64 v[6:7], s[14:15], 0, v[140:141]
	v_lshl_add_u64 v[4:5], s[14:15], 0, v[136:137]
	v_lshl_add_u64 v[2:3], s[12:13], 0, v[142:143]
	s_cmp_lg_u32 s0, 1
	v_lshl_add_u64 v[0:1], s[12:13], 0, v[138:139]
	s_cbranch_scc1 .LBB0_530
	s_barrier

.LBB0_600:
	v_writelane_b32 v255, s88, 20
	s_nop 1
	v_writelane_b32 v255, s89, 21
	s_or_b64 exec, exec, s[6:7]
	s_waitcnt lgkmcnt(0)
	v_mov_b32_e32 v0, v254
	v_mov_b64_e32 v[2:3], s[58:59]
	s_barrier
	flat_load_dwordx2 v[4:5], v[2:3] offset:192
	flat_load_dwordx2 v[6:7], v[2:3] offset:200
	flat_load_dwordx2 v[188:189], v[2:3] offset:208
	s_waitcnt vmcnt(0)
	s_add_u32 s66, s26, 0x13800000
	s_addc_u32 s67, s27, 0
	s_add_u32 s68, s26, 0x15900000
	s_addc_u32 s69, s27, 0
	s_add_u32 s64, s26, 0x2800000
	s_addc_u32 s65, s27, 0
	s_add_u32 s4, s26, 0x2dc00000
	s_addc_u32 s5, s27, 0
	v_writelane_b32 v255, s4, 22
	v_readfirstlane_b32 s0, v0
	s_waitcnt lgkmcnt(0)
	v_readfirstlane_b32 s71, v5
	v_writelane_b32 v255, s5, 23
	s_add_u32 s4, s26, 0x2b000000
	s_addc_u32 s5, s27, 0
	v_writelane_b32 v255, s4, 24
	v_readfirstlane_b32 s70, v4
	v_readfirstlane_b32 s73, v7
	v_writelane_b32 v255, s5, 25
	s_add_u32 s4, s26, 0x12a00000
	s_addc_u32 s5, s27, 0
	s_add_u32 s54, s26, 0x11200000
	v_writelane_b32 v255, s4, 26
	s_addc_u32 s55, s27, 0
	s_add_u32 s58, s26, 0x5c00000
	v_writelane_b32 v255, s5, 27
	s_addc_u32 s59, s27, 0
	v_readlane_b32 s4, v255, 7
	s_add_u32 s62, s26, 0x3000000
	v_readlane_b32 s5, v255, 8
	s_addc_u32 s63, s27, 0
	s_and_b64 vcc, exec, s[4:5]
	v_readfirstlane_b32 s72, v6
	s_cbranch_vccz .LBB0_732
	v_readlane_b32 s4, v255, 10
	v_readlane_b32 s5, v255, 11
	s_nop 1
	v_mov_b64_e32 v[2:3], s[4:5]
	flat_load_dwordx2 v[4:5], v[2:3] offset:80
	flat_load_dwordx2 v[6:7], v[2:3] offset:72
	flat_load_dwordx2 v[8:9], v[2:3] offset:64
	flat_load_dwordx2 v[10:11], v[2:3] offset:336
	flat_load_dwordx2 v[12:13], v[2:3] offset:232
	flat_load_dwordx2 v[14:15], v[2:3] offset:120
	s_waitcnt vmcnt(0) lgkmcnt(0)
	v_readfirstlane_b32 s76, v4
	v_readfirstlane_b32 s77, v5
	v_readfirstlane_b32 s78, v6
	v_readfirstlane_b32 s79, v7
	v_readfirstlane_b32 s80, v8
	v_readfirstlane_b32 s81, v9
	v_readfirstlane_b32 s82, v10
	v_readfirstlane_b32 s83, v11
	v_readfirstlane_b32 s84, v12
	v_readfirstlane_b32 s85, v13
	v_readfirstlane_b32 s6, v14
	v_readfirstlane_b32 s7, v15
	s_ashr_i32 s0, s0, 6
	v_and_b32_e32 v2, 15, v0
	v_bfe_u32 v131, v0, 4, 4
	s_add_i32 s23, s0, -4
	s_mulk_i32 s0, 0x2100
	v_lshlrev_b32_e32 v6, 3, v0
	v_lshlrev_b32_e32 v4, 8, v131
	v_lshlrev_b32_e32 v5, 4, v2
	s_add_i32 s0, s0, 0
	v_bfe_u32 v148, v0, 3, 3
	v_and_b32_e32 v6, 56, v6
	v_writelane_b32 v255, s6, 28
	s_movk_i32 s1, 0xff
	v_or_b32_e32 v136, 16, v131
	v_add3_u32 v141, 0, v4, v5
	v_and_b32_e32 v4, 0xf0, v0
	s_add_i32 s0, s0, 0x14c00
	v_mul_u32_u24_e32 v10, 0x84, v6
	v_lshlrev_b32_e32 v11, 2, v148
	v_writelane_b32 v255, s7, 29
	v_cmp_lt_i32_e64 s[6:7], s1, v0
	s_movk_i32 s1, 0x100
	v_lshlrev_b32_e32 v142, 2, v4
	v_lshlrev_b32_e32 v4, 8, v136
	v_add3_u32 v149, s0, v10, v11
	v_mov_b32_e32 v10, 5
	v_ashrrev_i32_e32 v99, 4, v0
	v_cmp_gt_i32_e64 s[8:9], s1, v0
	v_add3_u32 v145, 0, v4, v5
	v_and_b32_e32 v7, 7, v0
	v_bfe_u32 v147, v0, 5, 1
	v_and_b32_e32 v4, 31, v0
	v_lshlrev_b32_sdwa v153, v10, v0 dst_sel:DWORD dst_unused:UNUSED_PAD src0_sel:DWORD src1_sel:BYTE_0
	v_or_b32_sdwa v0, v0, s1 dst_sel:DWORD dst_unused:UNUSED_PAD src0_sel:BYTE_0 src1_sel:DWORD
	s_movk_i32 s4, 0x20ff
	v_lshrrev_b32_e32 v154, 4, v0
	v_lshlrev_b32_e32 v155, 5, v0
	v_mov_b32_e32 v0, 0xa040
	v_bitop3_b32 v140, v131, s4, 16 bitop3:0x36
	v_lshlrev_b32_e32 v3, 6, v131
	s_movk_i32 s4, 0xff40
	v_lshl_add_u32 v8, v4, 2, s0
	v_mul_u32_u24_e32 v9, 0x84, v147
	v_lshl_add_u32 v160, v99, 2, v0
	v_lshlrev_b32_e32 v0, 2, v7
	v_lshlrev_b32_e32 v98, 2, v2
	v_or_b32_e32 v137, 0x2000, v131
	v_xor_b32_e32 v138, 0x20ff, v131
	v_cmp_gt_u32_e64 s[10:11], 4, v2
	v_mov_b32_e32 v1, 0
	v_or_b32_e32 v139, 0x2010, v131
	s_mov_b32 s87, 0
	v_add3_u32 v143, 0, v142, v5
	v_lshlrev_b32_e32 v144, 6, v136
	v_mad_i32_i24 v146, v136, s4, v145
	v_or_b32_e32 v150, 8, v148
	v_or_b32_e32 v151, 16, v148
	v_or_b32_e32 v152, 24, v148
	v_or_b32_e32 v156, 0x1fe0, v131
	v_xor_b32_e32 v157, 31, v131
	v_or_b32_e32 v158, 0x1fe0, v154
	v_xor_b32_e32 v159, 31, v154
	v_or_b32_e32 v161, 0x100, v5
	v_lshl_or_b32 v162, v99, 5, v0
	s_mov_b32 s74, 0xf800000
	v_mov_b32_e32 v163, 0x260
	v_lshlrev_b32_e32 v100, 1, v2
	s_mov_b32 s75, 0xa800
	s_movk_i32 s40, 0x7fff
	s_mov_b32 s41, 0xac00
	s_movk_i32 s20, 0x15ff
	s_movk_i32 s21, 0x2bff
	s_movk_i32 s46, 0x41ff
	s_movk_i32 s47, 0x59ff
	s_movk_i32 s24, 0x61ff
	s_movk_i32 s44, 0x77ff
	s_mov_b32 s45, 0x8dff
	v_add_u32_e32 v164, v8, v9
	v_lshlrev_b32_e32 v102, 1, v6
	v_lshlrev_b32_e32 v104, 2, v4
	v_lshlrev_b32_e32 v165, 2, v3
	s_add_i32 s25, 0, 0x19000
	v_mov_b32_e32 v166, 7
	v_mov_b32_e32 v167, 0xa800
	s_mov_b32 s33, s2
	s_branch .LBB0_603

.LBB0_784:
	s_or_b64 exec, exec, s[6:7]
	v_readlane_b32 s0, v255, 10
	v_readlane_b32 s1, v255, 11
	s_waitcnt lgkmcnt(0)
	v_mov_b32_e32 v0, v254
	s_waitcnt vmcnt(0)
	v_mov_b64_e32 v[2:3], s[0:1]
	s_barrier
	flat_load_dwordx2 v[4:5], v[2:3] offset:200
	flat_load_dwordx2 v[6:7], v[2:3] offset:208
	flat_load_dwordx2 v[8:9], v[2:3] offset:216
	flat_load_dwordx2 v[2:3], v[2:3] offset:224
	s_waitcnt vmcnt(0)
	s_add_u32 s8, s26, 0xf200000
	v_readfirstlane_b32 s0, v0
	s_addc_u32 s9, s27, 0
	s_ashr_i32 s0, s0, 6
	v_readlane_b32 s1, v255, 6
	s_add_i32 s20, s0, s1
	s_cmp_lt_i32 s20, 0x10000
	s_waitcnt lgkmcnt(0)
	v_readfirstlane_b32 s11, v5
	v_readfirstlane_b32 s10, v4
	v_readfirstlane_b32 s13, v7
	v_readfirstlane_b32 s12, v6
	v_readfirstlane_b32 s15, v9
	v_readfirstlane_b32 s14, v8
	v_readfirstlane_b32 s17, v3
	v_readfirstlane_b32 s16, v2
	s_cbranch_scc0 .LBB0_787
	s_add_u32 s18, s26, 0xb200000
	s_addc_u32 s19, s27, 0
	v_lshlrev_b32_e32 v0, 2, v0
	s_lshl_b32 s1, s2, 11
	s_lshl_b32 s0, s0, 8
	v_and_b32_e32 v2, 0xfc, v0
	s_add_i32 s21, s1, s0
	s_lshl_b32 s23, s30, 11
	v_mov_b32_e32 v3, 0x3a27c5ac
	s_mov_b32 s24, 0xf800000
	v_mov_b32_e32 v4, 0x260
	v_mov_b32_e32 v1, 0
	s_movk_i32 s25, 0x1000
	s_and_b32 s0, s21, 0x700
	v_or_b32_e32 v124, s0, v2
	v_lshlrev_b32_e32 v120, 2, v124
	global_load_dwordx4 v[60:63], v120, s[14:15]
	global_load_dwordx4 v[64:67], v120, s[16:17]
	s_min_i32 s0, s20, 0xffff
	s_ashr_i32 s0, s0, 3
	s_lshl_b32 s1, s0, 11
	v_add_u32_e32 v121, s1, v124
	v_lshlrev_b32_e32 v98, 1, v121
	v_add_u32_e32 v121, 0x2000000, v121
	global_load_dwordx2 v[80:81], v98, s[38:39]
	global_load_dwordx2 v[82:83], v98, s[18:19]
	global_load_dwordx2 v[86:87], v98, s[68:69]
	global_load_dwordx2 v[88:89], v98, s[56:57]
	global_load_dword v94, v121, s[38:39]
	global_load_dword v95, v121, s[18:19]
	s_add_i32 s20, s20, s22
	s_min_i32 s0, s20, 0xffff
	s_ashr_i32 s0, s0, 3
	s_lshl_b32 s1, s0, 11
	v_add_u32_e32 v121, s1, v124
	v_lshlrev_b32_e32 v118, 1, v121
	v_add_u32_e32 v121, 0x2000000, v121
	global_load_dwordx2 v[100:101], v118, s[38:39]
	global_load_dwordx2 v[102:103], v118, s[18:19]
	global_load_dwordx2 v[106:107], v118, s[68:69]
	global_load_dwordx2 v[108:109], v118, s[56:57]
	global_load_dword v114, v121, s[38:39]
	global_load_dword v115, v121, s[18:19]
	s_add_i32 s20, s20, s22
	s_movk_i32 s4, 16

.Lprio_skip5:
	v_readlane_b32 s1, v255, 11
	v_mov_b32_e32 v8, v254
	s_nop 0
	v_mov_b64_e32 v[0:1], s[0:1]
	flat_load_dwordx2 v[0:1], v[0:1]
	s_waitcnt vmcnt(0)
	v_readlane_b32 s0, v255, 7
	v_readlane_b32 s1, v255, 8
	s_and_b64 vcc, exec, s[0:1]
	s_waitcnt lgkmcnt(0)
	v_readfirstlane_b32 s11, v1
	v_readfirstlane_b32 s20, v8
	v_readfirstlane_b32 s10, v0
	s_cbranch_vccz .LBB0_855
	v_lshlrev_b32_e32 v0, 4, v8
	v_add_u32_e32 v1, 0x2000, v0
	v_ashrrev_i32_e32 v2, 31, v1
	v_lshrrev_b32_e32 v2, 22, v2
	v_add_u32_e32 v2, v1, v2
	v_ashrrev_i32_e32 v9, 10, v2
	v_mul_i32_i24_e32 v2, 0x400, v9
	v_sub_u32_e32 v1, v1, v2
	v_lshrrev_b32_e32 v2, 4, v1
	v_bitop3_b32 v1, v2, v1, 32 bitop3:0x6c
	v_ashrrev_i32_e32 v2, 31, v1
	s_lshr_b32 s4, s3, 29
	v_lshrrev_b32_e32 v2, 26, v2
	s_add_i32 s4, s2, s4
	v_add_u32_e32 v2, v1, v2
	s_and_b32 s5, s4, -8
	s_ashr_i32 s1, s20, 6
	v_ashrrev_i32_e32 v10, 6, v2
	v_and_b32_e32 v2, 0xc0, v2
	s_sub_i32 s5, s2, s5
	s_ashr_i32 s0, s20, 8
	s_lshl_b32 s21, s1, 10
	v_sub_u32_e32 v1, v1, v2
	v_mov_b32_e32 v2, 1
	s_lshl_b32 s7, s5, 5
	s_ashr_i32 s4, s4, 3
	v_ashrrev_i16_sdwa v1, v2, sext(v1) dst_sel:DWORD dst_unused:UNUSED_PAD src0_sel:DWORD src1_sel:BYTE_0
	s_mul_i32 s6, s5, 33
	s_cmp_lt_i32 s5, 0
	v_bfe_i32 v12, v1, 0, 16
	v_bfe_i32 v1, v8, 27, 1
	s_cselect_b32 s5, s6, s7
	v_lshrrev_b32_e32 v1, 22, v1
	s_add_i32 s4, s5, s4
	v_add_u32_e32 v1, v0, v1
	s_ashr_i32 s5, s4, 31
	v_and_b32_e32 v1, 0xfffffc00, v1
	s_lshr_b32 s5, s5, 26
	v_sub_u32_e32 v0, v0, v1
	s_add_i32 s5, s4, s5
	v_lshrrev_b32_e32 v1, 4, v0
	s_ashr_i32 s6, s5, 6
	s_andn2_b32 s5, s5, 63
	v_bitop3_b32 v1, v1, v0, 32 bitop3:0x6c
	v_ashrrev_i32_e32 v0, 31, v0
	s_sub_i32 s5, s4, s5
	v_lshrrev_b32_e32 v0, 26, v0
	s_bfe_i32 s4, s5, 0x80000
	v_add_u32_e32 v0, v1, v0
	s_bfe_u32 s4, s4, 0x3000c
	v_lshlrev_b32_e32 v3, 3, v9
	v_ashrrev_i32_e32 v13, 6, v0
	v_ashrrev_i32_e32 v0, 31, v8
	s_add_i32 s7, s5, s4
	v_and_b32_e32 v3, 0xffff0, v3
	v_lshlrev_b32_e32 v4, 5, v9
	v_lshrrev_b32_e32 v0, 26, v0
	s_bfe_i32 s4, s7, 0x80000
	s_and_b32 s7, s7, 0xf8
	v_add_u32_e32 v3, v10, v3
	v_and_b32_e32 v11, 32, v4
	v_add_u32_e32 v0, v8, v0
	s_sub_i32 s5, s5, s7
	v_lshl_or_b32 v3, v3, 11, v11
	v_ashrrev_i32_e32 v14, 6, v0
	s_lshl_b32 s6, s6, 3
	s_sext_i32_i16 s4, s4
	s_sext_i32_i8 s5, s5
	v_add_lshl_u32 v128, v3, v12, 1
	v_lshlrev_b32_e32 v3, 5, v14
	s_lshr_b32 s4, s4, 3
	s_add_i32 s72, s6, s5
	v_lshlrev_b32_e32 v0, 3, v14
	v_and_b32_e32 v15, 32, v3
	v_mul_i32_i24_e32 v3, 64, v13
	s_ashr_i32 s73, s72, 31
	s_bfe_i64 s[12:13], s[4:5], 0x100000
	v_and_b32_e32 v0, 0xffff0, v0
	v_sub_u32_e32 v1, v1, v3
	s_lshl_b64 s[6:7], s[72:73], 20
	s_lshl_b64 s[12:13], s[12:13], 20
	v_add_u32_e32 v0, v13, v0
	v_ashrrev_i16_sdwa v1, v2, sext(v1) dst_sel:DWORD dst_unused:UNUSED_PAD src0_sel:DWORD src1_sel:BYTE_0
	s_add_u32 s50, s64, s12
	v_lshl_or_b32 v0, v0, 11, v15
	v_bfe_i32 v16, v1, 0, 16
	s_addc_u32 s51, s65, s13
	s_add_i32 s23, s21, 0
	v_add_lshl_u32 v130, v0, v16, 1
	s_add_i32 m0, s23, 0x10000
	s_load_dwordx2 s[12:13], s[88:89], 0x168
	global_load_lds_dwordx4 v130, s[50:51]
	s_add_i32 m0, s23, 0x12000
	s_add_u32 s74, s8, s6
	global_load_lds_dwordx4 v128, s[50:51]
	s_addc_u32 s75, s9, s7
	s_mov_b32 m0, s23
	s_add_i32 s24, s23, 0x2000
	global_load_lds_dwordx4 v130, s[74:75]
	s_mov_b32 m0, s24
	s_add_u32 s6, s50, 0x80000
	global_load_lds_dwordx4 v128, s[74:75]
	s_addc_u32 s7, s51, 0
	s_add_i32 m0, s23, 0x14000
	v_mov_b32_e32 v131, 0
	global_load_lds_dwordx4 v130, s[6:7]
	s_add_i32 m0, s23, 0x16000
	v_mov_b32_e32 v129, v131
	global_load_lds_dwordx4 v128, s[6:7]
	s_add_u32 s6, s74, 0x80000
	s_addc_u32 s7, s75, 0
	s_add_i32 s25, s23, 0x4000
	s_mov_b32 m0, s25
	s_add_i32 s28, s23, 0x6000
	global_load_lds_dwordx4 v130, s[6:7]
	s_mov_b32 m0, s28
	s_mov_b32 s29, 0
	global_load_lds_dwordx4 v128, s[6:7]
	v_lshl_add_u64 v[6:7], s[50:51], 0, v[130:131]
	v_lshl_add_u64 v[4:5], s[50:51], 0, v[128:129]
	v_lshl_add_u64 v[2:3], s[74:75], 0, v[130:131]
	s_cmp_lg_u32 s0, 1
	v_lshl_add_u64 v[0:1], s[74:75], 0, v[128:129]
	s_cbranch_scc1 .LBB0_842
	s_barrier

.LBB0_908:
	s_or_b64 exec, exec, s[6:7]
	v_readlane_b32 s0, v255, 10
	v_readlane_b32 s1, v255, 11
	s_waitcnt lgkmcnt(0)
	v_mov_b32_e32 v0, v254
	v_mov_b64_e32 v[2:3], s[0:1]
	s_barrier
	flat_load_dwordx2 v[2:3], v[2:3] offset:56
	s_waitcnt vmcnt(0)
	v_readfirstlane_b32 s0, v0
	s_ashr_i32 s6, s0, 6
	v_readlane_b32 s0, v255, 6
	s_lshl_b32 s52, s30, 4
	s_add_i32 s20, s6, s0
	s_cmpk_lt_i32 s20, 0x2000
	s_waitcnt lgkmcnt(0)
	v_readfirstlane_b32 s5, v3
	v_readfirstlane_b32 s4, v2
	s_cbranch_scc0 .LBB0_927
	v_lshlrev_b32_e32 v1, 4, v0
	v_and_b32_e32 v64, 0x3f0, v1
	v_mbcnt_lo_u32_b32 v1, -1, 0
	v_mbcnt_hi_u32_b32 v1, -1, v1
	v_and_b32_e32 v2, 64, v1
	v_add_u32_e32 v2, 64, v2
	v_xor_b32_e32 v3, 1, v1
	v_cmp_lt_i32_e32 vcc, v3, v2
	s_add_u32 s8, s26, 0x6000
	s_addc_u32 s9, s27, 0
	v_cndmask_b32_e32 v3, v1, v3, vcc
	v_lshlrev_b32_e32 v116, 2, v3
	v_xor_b32_e32 v3, 2, v1
	v_cmp_lt_i32_e32 vcc, v3, v2
	s_add_u32 s10, s26, 0x8000
	v_mov_b32_e32 v65, 0
	v_cndmask_b32_e32 v3, v1, v3, vcc
	v_lshlrev_b32_e32 v117, 2, v3
	v_xor_b32_e32 v3, 4, v1
	v_cmp_lt_i32_e32 vcc, v3, v2
	s_load_dwordx2 s[0:1], s[88:89], 0x168
	s_addc_u32 s11, s27, 0
	v_cndmask_b32_e32 v3, v1, v3, vcc
	v_lshlrev_b32_e32 v118, 2, v3
	v_xor_b32_e32 v3, 8, v1
	v_cmp_lt_i32_e32 vcc, v3, v2
	s_waitcnt lgkmcnt(0)
	v_lshl_add_u64 v[66:67], s[0:1], 0, v[64:65]
	v_lshl_add_u64 v[68:69], s[4:5], 0, v[64:65]
	v_cndmask_b32_e32 v3, v1, v3, vcc
	v_lshlrev_b32_e32 v119, 2, v3
	v_xor_b32_e32 v3, 16, v1
	v_cmp_lt_i32_e32 vcc, v3, v2
	v_lshl_add_u64 v[70:71], s[10:11], 0, v[64:65]
	v_lshl_add_u64 v[72:73], s[8:9], 0, v[64:65]
	v_cndmask_b32_e32 v3, v1, v3, vcc
	v_lshlrev_b32_e32 v120, 2, v3
	v_xor_b32_e32 v3, 32, v1
	v_cmp_lt_i32_e32 vcc, v3, v2
	v_or_b32_e32 v2, 0x400, v64
	v_and_b32_e32 v0, 63, v0
	v_cndmask_b32_e32 v1, v1, v3, vcc
	v_mov_b32_e32 v3, v65
	v_lshl_add_u64 v[74:75], s[10:11], 0, v[2:3]
	v_lshl_add_u64 v[76:77], s[8:9], 0, v[2:3]
	v_or_b32_e32 v2, 0x800, v64
	v_lshl_add_u64 v[78:79], s[10:11], 0, v[2:3]
	v_lshl_add_u64 v[80:81], s[8:9], 0, v[2:3]
	v_or_b32_e32 v2, 0xc00, v64
	v_lshl_add_u64 v[82:83], s[10:11], 0, v[2:3]
	v_lshl_add_u64 v[84:85], s[8:9], 0, v[2:3]
	v_or_b32_e32 v2, 0x1000, v64
	v_lshl_add_u64 v[86:87], s[4:5], 0, v[2:3]
	v_lshl_add_u64 v[88:89], s[10:11], 0, v[2:3]
	v_lshl_add_u64 v[90:91], s[8:9], 0, v[2:3]
	v_or_b32_e32 v2, 0x1400, v64
	v_lshl_add_u64 v[92:93], s[4:5], 0, v[2:3]
	v_lshl_add_u64 v[94:95], s[10:11], 0, v[2:3]
	v_lshl_add_u64 v[96:97], s[8:9], 0, v[2:3]
	v_or_b32_e32 v2, 0x1800, v64
	v_or_b32_e32 v64, 0x1c00, v64
	v_lshl_add_u64 v[98:99], s[4:5], 0, v[2:3]
	v_lshl_add_u64 v[104:105], s[4:5], 0, v[64:65]
	s_add_i32 s4, s20, s22
	s_ashr_i32 s5, s4, 31
	s_lshl_b64 s[4:5], s[4:5], 12
	v_lshl_add_u64 v[100:101], s[10:11], 0, v[2:3]
	v_lshl_add_u64 v[106:107], s[10:11], 0, v[64:65]
	s_add_u32 s10, s26, s4
	s_addc_u32 s11, s27, s5
	s_ashr_i32 s53, s52, 31
	v_readlane_b32 s4, v255, 6
	s_lshl_b64 s[12:13], s[52:53], 12
	s_ashr_i32 s5, s6, 31
	s_ashr_i32 s7, s4, 31
	s_add_u32 s4, s6, s4
	s_addc_u32 s5, s5, s7
	s_lshl_b64 s[6:7], s[4:5], 12
	s_add_u32 s6, s26, s6
	s_addc_u32 s7, s27, s7
	s_add_u32 s14, s6, 0x7200800
	s_addc_u32 s15, s7, 0
	s_lshl_b64 s[4:5], s[4:5], 13
	s_add_u32 s0, s0, s4
	v_lshlrev_b32_e32 v121, 2, v1
	v_lshl_add_u64 v[108:109], s[8:9], 0, v[64:65]
	v_lshlrev_b32_e32 v64, 3, v0
	v_lshlrev_b32_e32 v0, 4, v0
	v_mov_b32_e32 v1, v65
	s_addc_u32 s1, s1, s5
	v_lshl_add_u64 v[0:1], s[0:1], 0, v[0:1]
	s_mov_b64 s[0:1], 0x1c00
	s_movk_i32 s21, 0x1000
	v_lshl_add_u64 v[102:103], s[8:9], 0, v[2:3]
	v_lshl_add_u64 v[110:111], v[0:1], 0, s[0:1]
	s_lshl_b64 s[16:17], s[52:53], 13
	v_mov_b32_e32 v122, 0x358637bd
	s_mov_b32 s0, 0xf800000
	v_mov_b32_e32 v123, 0x260
	flat_load_dwordx4 v[150:153], v[68:69]
	global_load_dwordx4 v[154:157], v[70:71], off
	global_load_dwordx4 v[158:161], v[72:73], off
	global_load_dwordx4 v[162:165], v[74:75], off
	flat_load_dwordx4 v[166:169], v[68:69] offset:1024
	global_load_dwordx4 v[170:173], v[76:77], off
	global_load_dwordx4 v[174:177], v[78:79], off
	flat_load_dwordx4 v[178:181], v[68:69] offset:2048
	global_load_dwordx4 v[182:185], v[80:81], off
	global_load_dwordx4 v[186:189], v[82:83], off
	flat_load_dwordx4 v[190:193], v[68:69] offset:3072
	global_load_dwordx4 v[194:197], v[84:85], off
	global_load_dwordx4 v[198:201], v[88:89], off
	flat_load_dwordx4 v[202:205], v[86:87]
	global_load_dwordx4 v[206:209], v[90:91], off
	global_load_dwordx4 v[210:213], v[94:95], off
	flat_load_dwordx4 v[214:217], v[92:93]
	global_load_dwordx4 v[218:221], v[96:97], off
	global_load_dwordx4 v[222:225], v[100:101], off
	flat_load_dwordx4 v[226:229], v[98:99]
	global_load_dwordx4 v[230:233], v[102:103], off
	global_load_dwordx4 v[234:237], v[106:107], off
	flat_load_dwordx4 v[238:241], v[104:105]
	global_load_dwordx4 v[242:245], v[108:109], off
	s_waitcnt vmcnt(0) lgkmcnt(0)
	s_branch .LBB0_911

.LBB0_1012:
	v_readlane_b32 s0, v255, 10
	v_readlane_b32 s1, v255, 11
	v_lshl_add_u32 v24, v128, 2, 0
	s_nop 0
	v_mov_b64_e32 v[0:1], s[0:1]
	flat_load_dwordx2 v[2:3], v[0:1] offset:8
	flat_load_dwordx2 v[4:5], v[0:1] offset:32
	flat_load_dwordx2 v[6:7], v[0:1] offset:40
	s_waitcnt vmcnt(0)
	s_movk_i32 s0, 0x800
	v_cmp_gt_i32_e32 vcc, s0, v128
	s_waitcnt lgkmcnt(0)
	s_barrier
	v_readfirstlane_b32 s7, v3
	v_readfirstlane_b32 s6, v2
	v_readfirstlane_b32 s5, v5
	v_readfirstlane_b32 s4, v4
	v_readfirstlane_b32 s10, v7
	v_readfirstlane_b32 s11, v6
	s_and_saveexec_b64 s[0:1], vcc
	s_cbranch_execz .LBB0_1015
	v_ashrrev_i32_e32 v129, 31, v128
	v_add_u32_e32 v2, 0xfffffe00, v128
	v_lshl_add_u64 v[0:1], v[128:129], 2, s[6:7]
	s_mov_b64 s[6:7], 0
	s_mov_b32 s12, 0xbfb8aa3b
	s_mov_b32 s13, 0x42ce8ed0
	s_mov_b32 s15, 0xc2b17218
	v_mov_b32_e32 v3, 0x7f800000
	s_mov_b64 s[8:9], 0x800
	s_movk_i32 s16, 0x5ff
	v_mov_b32_e32 v4, v24

.LBB0_1156:
	s_or_b64 exec, exec, s[6:7]
	s_waitcnt lgkmcnt(0)
	v_mov_b32_e32 v0, v254
	v_mov_b64_e32 v[2:3], s[40:41]
	s_barrier
	flat_load_dwordx2 v[2:3], v[2:3] offset:48
	s_waitcnt vmcnt(0)
	v_readfirstlane_b32 s0, v0
	s_ashr_i32 s6, s0, 6
	v_readlane_b32 s0, v255, 6
	s_add_i32 s0, s6, s0
	s_cmpk_lt_i32 s0, 0x2000
	s_waitcnt lgkmcnt(0)
	v_readfirstlane_b32 s1, v3
	v_readfirstlane_b32 s7, v2
	s_cbranch_scc0 .LBB0_1175
	v_lshlrev_b32_e32 v1, 4, v0
	v_and_b32_e32 v64, 0x3f0, v1
	v_mbcnt_lo_u32_b32 v1, -1, 0
	v_mbcnt_hi_u32_b32 v1, -1, v1
	v_and_b32_e32 v2, 64, v1
	v_add_u32_e32 v2, 64, v2
	v_xor_b32_e32 v3, 1, v1
	v_cmp_lt_i32_e32 vcc, v3, v2
	s_add_u32 s8, s7, 0x2000
	s_addc_u32 s9, s1, 0
	v_cndmask_b32_e32 v3, v1, v3, vcc
	v_lshlrev_b32_e32 v122, 2, v3
	v_xor_b32_e32 v3, 2, v1
	v_cmp_lt_i32_e32 vcc, v3, v2
	s_add_u32 s10, s26, 0x1a000
	s_addc_u32 s11, s27, 0
	v_cndmask_b32_e32 v3, v1, v3, vcc
	v_lshlrev_b32_e32 v123, 2, v3
	v_xor_b32_e32 v3, 4, v1
	v_cmp_lt_i32_e32 vcc, v3, v2
	s_add_u32 s12, s26, 0x18000
	v_mov_b32_e32 v65, 0
	v_cndmask_b32_e32 v3, v1, v3, vcc
	v_lshlrev_b32_e32 v124, 2, v3
	v_xor_b32_e32 v3, 8, v1
	v_cmp_lt_i32_e32 vcc, v3, v2
	s_load_dwordx2 s[4:5], s[88:89], 0x168
	s_addc_u32 s13, s27, 0
	v_cndmask_b32_e32 v3, v1, v3, vcc
	v_lshlrev_b32_e32 v125, 2, v3
	v_xor_b32_e32 v3, 16, v1
	v_cmp_lt_i32_e32 vcc, v3, v2
	s_waitcnt lgkmcnt(0)
	v_lshl_add_u64 v[66:67], s[4:5], 0, v[64:65]
	v_lshl_add_u64 v[68:69], s[8:9], 0, v[64:65]
	v_cndmask_b32_e32 v3, v1, v3, vcc
	v_lshlrev_b32_e32 v126, 2, v3
	v_xor_b32_e32 v3, 32, v1
	v_cmp_lt_i32_e32 vcc, v3, v2
	v_or_b32_e32 v2, 0x400, v64
	v_lshl_add_u64 v[70:71], s[10:11], 0, v[64:65]
	v_cndmask_b32_e32 v1, v1, v3, vcc
	v_mov_b32_e32 v3, v65
	v_lshl_add_u64 v[74:75], s[8:9], 0, v[2:3]
	v_lshl_add_u64 v[76:77], s[10:11], 0, v[2:3]
	v_lshl_add_u64 v[78:79], s[12:13], 0, v[2:3]
	v_or_b32_e32 v2, 0x800, v64
	v_lshl_add_u64 v[80:81], s[8:9], 0, v[2:3]
	v_lshl_add_u64 v[82:83], s[10:11], 0, v[2:3]
	v_lshl_add_u64 v[84:85], s[12:13], 0, v[2:3]
	v_or_b32_e32 v2, 0xc00, v64
	v_lshl_add_u64 v[86:87], s[8:9], 0, v[2:3]
	v_lshl_add_u64 v[88:89], s[10:11], 0, v[2:3]
	v_lshl_add_u64 v[90:91], s[12:13], 0, v[2:3]
	v_or_b32_e32 v2, 0x1000, v64
	v_lshl_add_u64 v[92:93], s[8:9], 0, v[2:3]
	v_lshl_add_u64 v[94:95], s[10:11], 0, v[2:3]
	v_lshl_add_u64 v[96:97], s[12:13], 0, v[2:3]
	v_or_b32_e32 v2, 0x1400, v64
	v_lshl_add_u64 v[72:73], s[12:13], 0, v[64:65]
	v_lshl_add_u64 v[98:99], s[8:9], 0, v[2:3]
	v_lshl_add_u64 v[100:101], s[10:11], 0, v[2:3]
	v_lshl_add_u64 v[102:103], s[12:13], 0, v[2:3]
	v_or_b32_e32 v2, 0x1800, v64
	v_or_b32_e32 v64, 0x1c00, v64
	v_lshl_add_u64 v[104:105], s[8:9], 0, v[2:3]
	v_lshl_add_u64 v[110:111], s[8:9], 0, v[64:65]
	s_add_i32 s8, s0, s22
	s_ashr_i32 s9, s8, 31
	s_lshl_b64 s[8:9], s[8:9], 12
	v_lshl_add_u64 v[106:107], s[10:11], 0, v[2:3]
	v_lshl_add_u64 v[112:113], s[10:11], 0, v[64:65]
	s_add_u32 s10, s26, s8
	s_addc_u32 s11, s27, s9
	s_ashr_i32 s53, s52, 31
	v_readlane_b32 s9, v255, 6
	v_lshl_add_u64 v[108:109], s[12:13], 0, v[2:3]
	v_lshl_add_u64 v[114:115], s[12:13], 0, v[64:65]
	s_lshl_b64 s[12:13], s[52:53], 12
	s_ashr_i32 s7, s6, 31
	s_ashr_i32 s8, s9, 31
	s_add_u32 s6, s6, s9
	s_addc_u32 s7, s7, s8
	s_lshl_b64 s[8:9], s[6:7], 12
	s_add_u32 s8, s26, s8
	s_addc_u32 s9, s27, s9
	s_add_u32 s14, s8, 0x7200800
	s_addc_u32 s15, s9, 0
	s_lshl_b64 s[6:7], s[6:7], 13
	v_and_b32_e32 v0, 63, v0
	s_add_u32 s4, s4, s6
	v_lshlrev_b32_e32 v127, 2, v1
	v_lshlrev_b32_e32 v64, 3, v0
	v_lshlrev_b32_e32 v0, 4, v0
	v_mov_b32_e32 v1, v65
	s_addc_u32 s5, s5, s7
	v_lshl_add_u64 v[0:1], s[4:5], 0, v[0:1]
	s_mov_b64 s[4:5], 0x1c00
	s_movk_i32 s1, 0x1000
	v_lshl_add_u64 v[116:117], v[0:1], 0, s[4:5]
	s_lshl_b64 s[16:17], s[52:53], 13
	v_mov_b32_e32 v128, 0x358637bd
	s_mov_b32 s4, 0xf800000
	v_mov_b32_e32 v129, 0x260
	flat_load_dwordx4 v[150:153], v[68:69]
	global_load_dwordx4 v[154:157], v[70:71], off
	global_load_dwordx4 v[158:161], v[72:73], off
	global_load_dwordx4 v[162:165], v[76:77], off
	flat_load_dwordx4 v[166:169], v[74:75]
	global_load_dwordx4 v[170:173], v[78:79], off
	global_load_dwordx4 v[174:177], v[82:83], off
	flat_load_dwordx4 v[178:181], v[80:81]
	global_load_dwordx4 v[182:185], v[84:85], off
	global_load_dwordx4 v[186:189], v[88:89], off
	flat_load_dwordx4 v[190:193], v[86:87]
	global_load_dwordx4 v[194:197], v[90:91], off
	global_load_dwordx4 v[198:201], v[94:95], off
	flat_load_dwordx4 v[202:205], v[92:93]
	global_load_dwordx4 v[206:209], v[96:97], off
	global_load_dwordx4 v[210:213], v[100:101], off
	flat_load_dwordx4 v[214:217], v[98:99]
	global_load_dwordx4 v[218:221], v[102:103], off
	global_load_dwordx4 v[222:225], v[106:107], off
	flat_load_dwordx4 v[226:229], v[104:105]
	global_load_dwordx4 v[230:233], v[108:109], off
	global_load_dwordx4 v[234:237], v[112:113], off
	flat_load_dwordx4 v[238:241], v[110:111]
	global_load_dwordx4 v[242:245], v[114:115], off
	s_waitcnt vmcnt(0) lgkmcnt(0)
	s_branch .LBB0_1159

.Lprio_skip10:
	v_mov_b32_e32 v9, v254
	v_mov_b64_e32 v[0:1], s[40:41]
	flat_load_dwordx2 v[0:1], v[0:1] offset:240
	s_waitcnt vmcnt(0)
	s_cmpk_lt_i32 s2, 0x300
	s_waitcnt lgkmcnt(0)
	v_readfirstlane_b32 s9, v1
	v_readfirstlane_b32 s8, v0
	v_readfirstlane_b32 s23, v9
	s_cbranch_scc0 .LBB0_1239
	v_lshlrev_b32_e32 v0, 4, v9
	v_add_u32_e32 v1, 0x2000, v0
	v_ashrrev_i32_e32 v2, 31, v1
	v_lshrrev_b32_e32 v2, 22, v2
	v_add_u32_e32 v2, v1, v2
	v_ashrrev_i32_e32 v8, 10, v2
	v_mul_i32_i24_e32 v2, 0x400, v8
	v_sub_u32_e32 v1, v1, v2
	v_lshrrev_b32_e32 v2, 4, v1
	v_bitop3_b32 v1, v2, v1, 32 bitop3:0x6c
	v_ashrrev_i32_e32 v2, 31, v1
	v_lshrrev_b32_e32 v2, 26, v2
	v_add_u32_e32 v2, v1, v2
	v_lshlrev_b32_e32 v3, 3, v8
	v_ashrrev_i32_e32 v10, 6, v2
	v_and_b32_e32 v3, -16, v3
	v_add_u32_e32 v3, v10, v3
	v_and_b32_e32 v4, 3, v10
	s_mov_b32 s4, 0xfffe0
	v_lshrrev_b32_e32 v5, 2, v3
	v_lshlrev_b32_e32 v6, 1, v3
	v_and_b32_e32 v2, 0xc0, v2
	v_and_or_b32 v4, v3, s4, v4
	v_and_b32_e32 v5, 4, v5
	v_and_b32_e32 v6, 24, v6
	v_sub_u32_e32 v1, v1, v2
	v_mov_b32_e32 v2, 1
	v_or3_b32 v4, v4, v5, v6
	v_lshlrev_b32_e32 v5, 5, v8
	v_ashrrev_i16_sdwa v1, v2, sext(v1) dst_sel:DWORD dst_unused:UNUSED_PAD src0_sel:DWORD src1_sel:BYTE_0
	v_and_b32_e32 v5, 32, v5
	v_bfe_i32 v11, v1, 0, 16
	v_add_lshl_u32 v1, v5, v11, 1
	v_lshl_add_u32 v136, v4, 12, v1
	v_lshl_add_u32 v138, v3, 12, v1
	v_bfe_i32 v1, v9, 27, 1
	v_lshrrev_b32_e32 v1, 22, v1
	v_add_u32_e32 v1, v0, v1
	v_and_b32_e32 v1, 0xfffffc00, v1
	v_sub_u32_e32 v0, v0, v1
	v_lshrrev_b32_e32 v1, 4, v0
	v_bitop3_b32 v1, v1, v0, 32 bitop3:0x6c
	v_ashrrev_i32_e32 v0, 31, v0
	v_lshrrev_b32_e32 v0, 26, v0
	v_add_u32_e32 v0, v1, v0
	v_ashrrev_i32_e32 v12, 6, v0
	v_ashrrev_i32_e32 v0, 31, v9
	v_lshrrev_b32_e32 v0, 26, v0
	v_add_u32_e32 v0, v9, v0
	v_ashrrev_i32_e32 v13, 6, v0
	v_lshlrev_b32_e32 v0, 3, v13
	v_and_b32_e32 v0, -16, v0
	v_add_u32_e32 v0, v12, v0
	v_and_b32_e32 v3, 3, v12
	v_and_or_b32 v3, v0, s4, v3
	s_lshr_b32 s4, s3, 29
	s_add_i32 s4, s2, s4
	s_ashr_i32 s1, s23, 6
	s_ashr_i32 s5, s4, 3
	s_and_b32 s4, s4, -8
	s_ashr_i32 s0, s23, 8
	s_lshl_b32 s24, s1, 10
	s_sub_i32 s4, s2, s4
	s_cmp_lt_i32 s4, 0
	s_movk_i32 s25, 0x61
	s_cselect_b32 s6, s25, 0x60
	s_mul_i32 s4, s4, s6
	s_add_i32 s4, s4, s5
	s_mul_hi_i32 s5, s4, 0x2aaaaaab
	s_lshr_b32 s6, s5, 31
	s_ashr_i32 s5, s5, 5
	s_add_i32 s5, s5, s6
	s_lshl_b32 s6, s5, 3
	s_mulk_i32 s5, 0xc0
	s_sub_i32 s5, s4, s5
	s_sext_i32_i16 s4, s5
	s_bfe_u32 s4, s4, 0x3001c
	s_add_i32 s7, s5, s4
	s_sext_i32_i16 s4, s7
	s_and_b32 s7, s7, 0xfff8
	v_lshrrev_b32_e32 v4, 2, v0
	v_lshlrev_b32_e32 v5, 1, v0
	s_sub_i32 s5, s5, s7
	v_and_b32_e32 v4, 4, v4
	v_and_b32_e32 v5, 24, v5
	s_sext_i32_i16 s5, s5
	v_or3_b32 v3, v3, v4, v5
	v_mul_i32_i24_e32 v5, 64, v12
	s_lshr_b32 s4, s4, 3
	s_add_i32 s20, s6, s5
	v_sub_u32_e32 v1, v1, v5
	s_ashr_i32 s21, s20, 31
	s_bfe_i64 s[10:11], s[4:5], 0x100000
	v_lshlrev_b32_e32 v4, 5, v13
	v_ashrrev_i16_sdwa v1, v2, sext(v1) dst_sel:DWORD dst_unused:UNUSED_PAD src0_sel:DWORD src1_sel:BYTE_0
	s_lshl_b64 s[6:7], s[20:21], 20
	s_lshl_b64 s[10:11], s[10:11], 20
	v_and_b32_e32 v4, 32, v4
	v_bfe_i32 v14, v1, 0, 16
	s_add_u32 s58, s54, s10
	v_add_lshl_u32 v1, v4, v14, 1
	s_addc_u32 s59, s55, s11
	s_add_i32 s21, s24, 0
	v_lshl_add_u32 v140, v3, 12, v1
	s_add_i32 m0, s21, 0x10000
	v_lshl_add_u32 v142, v0, 12, v1
	global_load_lds_dwordx4 v140, s[58:59]
	s_add_i32 m0, s21, 0x12000
	s_add_u32 s36, s38, s6
	global_load_lds_dwordx4 v136, s[58:59]
	s_addc_u32 s37, s39, s7
	s_mov_b32 m0, s21
	s_add_i32 s28, s21, 0x2000
	global_load_lds_dwordx4 v142, s[36:37]
	s_mov_b32 m0, s28
	s_add_u32 s6, s58, 0x80000
	global_load_lds_dwordx4 v138, s[36:37]
	s_addc_u32 s7, s59, 0
	s_add_i32 m0, s21, 0x14000
	v_mov_b32_e32 v141, 0
	global_load_lds_dwordx4 v140, s[6:7]
	s_add_i32 m0, s21, 0x16000
	v_mov_b32_e32 v137, v141
	global_load_lds_dwordx4 v136, s[6:7]
	s_add_u32 s6, s36, 0x80000
	s_addc_u32 s7, s37, 0
	s_add_i32 s29, s21, 0x4000
	s_mov_b32 m0, s29
	s_add_i32 s33, s21, 0x6000
	global_load_lds_dwordx4 v142, s[6:7]
	s_mov_b32 m0, s33
	v_mov_b32_e32 v143, v141
	global_load_lds_dwordx4 v138, s[6:7]
	v_mov_b32_e32 v139, v141
	s_mov_b32 s40, 0
	v_lshl_add_u64 v[6:7], s[58:59], 0, v[140:141]
	v_lshl_add_u64 v[4:5], s[58:59], 0, v[136:137]
	v_lshl_add_u64 v[2:3], s[36:37], 0, v[142:143]
	s_cmp_lg_u32 s0, 1
	v_lshl_add_u64 v[0:1], s[36:37], 0, v[138:139]
	s_cbranch_scc1 .LBB0_1230
	s_barrier

.LBB0_1292:
	s_or_b64 exec, exec, s[6:7]
	s_waitcnt lgkmcnt(0)
	v_mov_b32_e32 v0, v254
	v_mov_b64_e32 v[2:3], s[40:41]
	s_barrier
	flat_load_dwordx2 v[4:5], v[2:3] offset:248
	flat_load_dwordx2 v[6:7], v[2:3] offset:256
	s_waitcnt vmcnt(0)
	s_add_u32 s46, s26, 0xd200000
	s_addc_u32 s47, s27, 0
	s_add_u32 s54, s26, 0x9200000
	s_addc_u32 s55, s27, 0
	s_cmpk_lt_i32 s2, 0x1000
	s_waitcnt lgkmcnt(0)
	v_readfirstlane_b32 s9, v5
	v_readfirstlane_b32 s8, v4
	v_readfirstlane_b32 s11, v7
	v_readfirstlane_b32 s10, v6
	s_cbranch_scc0 .LBB0_1319
	v_ashrrev_i32_e32 v5, 4, v0
	v_lshlrev_b32_e32 v1, 2, v0
	v_ashrrev_i32_e32 v55, 3, v0
	v_lshlrev_b32_e32 v0, 3, v0
	s_add_u32 s12, s8, 0x6000
	v_and_b32_e32 v4, 56, v0
	s_movk_i32 s4, 0x41
	v_and_b32_e32 v54, 60, v1
	s_addc_u32 s13, s9, 0
	v_mad_u64_u32 v[0:1], s[0:1], v55, s4, v[4:5]
	s_add_u32 s14, s8, 0xc000
	v_lshl_add_u32 v56, v0, 2, 0
	v_mad_u32_u24 v0, v54, s4, v5
	s_addc_u32 s15, s9, 0
	v_mov_b32_e32 v7, 0
	v_or_b32_e32 v57, 0x800, v54
	v_or_b32_e32 v58, 0x1000, v54
	v_lshl_add_u32 v59, v0, 2, 0
	s_lshl_b32 s4, s2, 1
	s_lshl_b32 s5, s30, 1
	s_lshl_b32 s18, s2, 6
	s_lshl_b32 s19, s30, 6
	s_movk_i32 s20, 0x3000
	v_mov_b64_e32 v[8:9], s[48:49]
	s_movk_i32 s21, 0x1fff
	s_mov_b32 s23, 0xd200000
	s_mov_b32 s24, s2
	s_branch .LBB0_1295

.LBB0_1371:
	s_or_b64 exec, exec, s[6:7]
	v_mov_b32_e32 v32, v254
	s_waitcnt lgkmcnt(0)
	v_mov_b64_e32 v[0:1], s[40:41]
	s_barrier
	flat_load_dwordx2 v[0:1], v[0:1] offset:328
	s_waitcnt vmcnt(0)
	s_movk_i32 s0, 0x800
	v_cmp_gt_i32_e32 vcc, s0, v32
	s_waitcnt lgkmcnt(0)
	v_readfirstlane_b32 s23, v1
	v_readfirstlane_b32 s24, v0
	s_and_saveexec_b64 s[0:1], vcc
	s_cbranch_execz .LBB0_1374
	v_ashrrev_i32_e32 v33, 31, v32
	v_lshl_add_u64 v[0:1], v[32:33], 3, s[26:27]
	s_mov_b64 s[4:5], 0x50000
	v_lshl_add_u32 v3, v32, 3, 0
	v_add_u32_e32 v2, 0xfffffe00, v32
	v_lshl_add_u64 v[0:1], v[0:1], 0, s[4:5]
	v_add_u32_e32 v3, 0x20000, v3
	s_mov_b64 s[4:5], 0
	s_mov_b64 s[6:7], 0x1000
	s_movk_i32 s8, 0x5ff

.Lprio_skip14:
	v_readlane_b32 s0, v255, 7
	v_mov_b64_e32 v[0:1], s[58:59]
	flat_load_dwordx2 v[0:1], v[0:1] offset:344
	s_waitcnt vmcnt(0)
	v_mov_b32_e32 v8, v254
	v_readlane_b32 s1, v255, 8
	s_and_b64 vcc, exec, s[0:1]
	s_waitcnt lgkmcnt(0)
	v_readfirstlane_b32 s11, v1
	v_readfirstlane_b32 s23, v8
	v_readfirstlane_b32 s10, v0
	s_cbranch_vccz .LBB0_1545
	v_lshlrev_b32_e32 v0, 4, v8
	v_add_u32_e32 v1, 0x2000, v0
	v_ashrrev_i32_e32 v2, 31, v1
	v_lshrrev_b32_e32 v2, 22, v2
	v_add_u32_e32 v2, v1, v2
	v_ashrrev_i32_e32 v9, 10, v2
	v_mul_i32_i24_e32 v2, 0x400, v9
	v_sub_u32_e32 v1, v1, v2
	v_lshrrev_b32_e32 v2, 4, v1
	v_bitop3_b32 v1, v2, v1, 32 bitop3:0x6c
	v_ashrrev_i32_e32 v2, 31, v1
	s_lshr_b32 s4, s3, 29
	v_lshrrev_b32_e32 v2, 26, v2
	s_add_i32 s4, s2, s4
	v_add_u32_e32 v2, v1, v2
	s_and_b32 s5, s4, -8
	s_ashr_i32 s1, s23, 6
	v_ashrrev_i32_e32 v10, 6, v2
	v_and_b32_e32 v2, 0xc0, v2
	s_sub_i32 s5, s2, s5
	s_ashr_i32 s0, s23, 8
	s_lshl_b32 s24, s1, 10
	v_sub_u32_e32 v1, v1, v2
	v_mov_b32_e32 v2, 1
	s_lshl_b32 s7, s5, 5
	s_ashr_i32 s4, s4, 3
	v_ashrrev_i16_sdwa v1, v2, sext(v1) dst_sel:DWORD dst_unused:UNUSED_PAD src0_sel:DWORD src1_sel:BYTE_0
	s_mul_i32 s6, s5, 33
	s_cmp_lt_i32 s5, 0
	v_bfe_i32 v12, v1, 0, 16
	v_bfe_i32 v1, v8, 27, 1
	s_cselect_b32 s5, s6, s7
	v_lshrrev_b32_e32 v1, 22, v1
	s_add_i32 s4, s5, s4
	v_add_u32_e32 v1, v0, v1
	s_ashr_i32 s5, s4, 31
	v_and_b32_e32 v1, 0xfffffc00, v1
	s_lshr_b32 s5, s5, 26
	v_sub_u32_e32 v0, v0, v1
	s_add_i32 s5, s4, s5
	v_lshrrev_b32_e32 v1, 4, v0
	s_ashr_i32 s6, s5, 6
	s_andn2_b32 s5, s5, 63
	v_bitop3_b32 v1, v1, v0, 32 bitop3:0x6c
	v_ashrrev_i32_e32 v0, 31, v0
	s_sub_i32 s5, s4, s5
	v_lshrrev_b32_e32 v0, 26, v0
	s_bfe_i32 s4, s5, 0x80000
	v_add_u32_e32 v0, v1, v0
	s_bfe_u32 s4, s4, 0x3000c
	v_lshlrev_b32_e32 v3, 3, v9
	v_ashrrev_i32_e32 v13, 6, v0
	v_ashrrev_i32_e32 v0, 31, v8
	s_add_i32 s7, s5, s4
	v_and_b32_e32 v3, 0xffff0, v3
	v_lshlrev_b32_e32 v4, 5, v9
	v_lshrrev_b32_e32 v0, 26, v0
	s_bfe_i32 s4, s7, 0x80000
	s_and_b32 s7, s7, 0xf8
	v_add_u32_e32 v3, v10, v3
	v_and_b32_e32 v11, 32, v4
	v_add_u32_e32 v0, v8, v0
	s_sub_i32 s5, s5, s7
	v_lshl_or_b32 v3, v3, 11, v11
	v_ashrrev_i32_e32 v14, 6, v0
	s_lshl_b32 s6, s6, 3
	s_sext_i32_i16 s4, s4
	s_sext_i32_i8 s5, s5
	v_add_lshl_u32 v138, v3, v12, 1
	v_lshlrev_b32_e32 v3, 5, v14
	s_lshr_b32 s4, s4, 3
	s_add_i32 s66, s6, s5
	v_lshlrev_b32_e32 v0, 3, v14
	v_and_b32_e32 v15, 32, v3
	v_mul_i32_i24_e32 v3, 64, v13
	s_ashr_i32 s67, s66, 31
	s_bfe_i64 s[8:9], s[4:5], 0x100000
	v_and_b32_e32 v0, 0xffff0, v0
	v_sub_u32_e32 v1, v1, v3
	s_lshl_b64 s[6:7], s[66:67], 20
	s_lshl_b64 s[8:9], s[8:9], 20
	v_readlane_b32 s12, v255, 26
	v_add_u32_e32 v0, v13, v0
	v_ashrrev_i16_sdwa v1, v2, sext(v1) dst_sel:DWORD dst_unused:UNUSED_PAD src0_sel:DWORD src1_sel:BYTE_0
	v_readlane_b32 s13, v255, 27
	s_add_u32 s68, s12, s8
	v_lshl_or_b32 v0, v0, 11, v15
	v_bfe_i32 v16, v1, 0, 16
	s_addc_u32 s69, s13, s9
	s_add_i32 s25, s24, 0
	v_add_lshl_u32 v140, v0, v16, 1
	s_add_i32 m0, s25, 0x10000
	s_load_dwordx2 s[12:13], s[88:89], 0x168
	global_load_lds_dwordx4 v140, s[68:69]
	s_add_i32 m0, s25, 0x12000
	s_add_u32 s8, s38, s6
	global_load_lds_dwordx4 v138, s[68:69]
	s_addc_u32 s9, s39, s7
	s_mov_b32 m0, s25
	s_add_i32 s28, s25, 0x2000
	global_load_lds_dwordx4 v140, s[8:9]
	s_mov_b32 m0, s28
	s_add_u32 s6, s68, 0x80000
	global_load_lds_dwordx4 v138, s[8:9]
	s_addc_u32 s7, s69, 0
	s_add_i32 m0, s25, 0x14000
	v_mov_b32_e32 v141, 0
	global_load_lds_dwordx4 v140, s[6:7]
	s_add_i32 m0, s25, 0x16000
	v_mov_b32_e32 v139, v141
	global_load_lds_dwordx4 v138, s[6:7]
	s_add_u32 s6, s8, 0x80000
	s_addc_u32 s7, s9, 0
	s_add_i32 s29, s25, 0x4000
	s_mov_b32 m0, s29
	s_add_i32 s33, s25, 0x6000
	global_load_lds_dwordx4 v140, s[6:7]
	s_mov_b32 m0, s33
	s_mov_b32 s36, 0
	global_load_lds_dwordx4 v138, s[6:7]
	v_lshl_add_u64 v[6:7], s[68:69], 0, v[140:141]
	v_lshl_add_u64 v[4:5], s[68:69], 0, v[138:139]
	v_lshl_add_u64 v[2:3], s[8:9], 0, v[140:141]
	s_cmp_lg_u32 s0, 1
	v_lshl_add_u64 v[0:1], s[8:9], 0, v[138:139]
	s_cbranch_scc1 .LBB0_1524
	s_barrier

.LBB0_1598:
	s_or_b64 exec, exec, s[6:7]
	s_waitcnt lgkmcnt(0)
	v_mov_b32_e32 v0, v254
	v_mov_b64_e32 v[2:3], s[58:59]
	s_barrier
	flat_load_dwordx2 v[2:3], v[2:3] offset:56
	s_waitcnt vmcnt(0)
	v_readfirstlane_b32 s0, v0
	s_ashr_i32 s6, s0, 6
	v_readlane_b32 s0, v255, 6
	s_add_i32 s0, s6, s0
	s_cmpk_lt_i32 s0, 0x2000
	s_waitcnt lgkmcnt(0)
	v_readfirstlane_b32 s1, v3
	v_readfirstlane_b32 s7, v2
	s_cbranch_scc0 .LBB0_1617
	v_lshlrev_b32_e32 v1, 4, v0
	v_and_b32_e32 v64, 0x3f0, v1
	v_mbcnt_lo_u32_b32 v1, -1, 0
	v_mbcnt_hi_u32_b32 v1, -1, v1
	v_and_b32_e32 v2, 64, v1
	v_add_u32_e32 v2, 64, v2
	v_xor_b32_e32 v3, 1, v1
	v_cmp_lt_i32_e32 vcc, v3, v2
	s_add_u32 s8, s7, 0x2000
	s_addc_u32 s9, s1, 0
	v_cndmask_b32_e32 v3, v1, v3, vcc
	v_lshlrev_b32_e32 v122, 2, v3
	v_xor_b32_e32 v3, 2, v1
	v_cmp_lt_i32_e32 vcc, v3, v2
	s_add_u32 s10, s26, 0x1e000
	s_addc_u32 s11, s27, 0
	v_cndmask_b32_e32 v3, v1, v3, vcc
	v_lshlrev_b32_e32 v123, 2, v3
	v_xor_b32_e32 v3, 4, v1
	v_cmp_lt_i32_e32 vcc, v3, v2
	s_add_u32 s12, s26, 0x20000
	v_mov_b32_e32 v65, 0
	v_cndmask_b32_e32 v3, v1, v3, vcc
	v_lshlrev_b32_e32 v124, 2, v3
	v_xor_b32_e32 v3, 8, v1
	v_cmp_lt_i32_e32 vcc, v3, v2
	s_load_dwordx2 s[4:5], s[88:89], 0x168
	s_addc_u32 s13, s27, 0
	v_cndmask_b32_e32 v3, v1, v3, vcc
	v_lshlrev_b32_e32 v125, 2, v3
	v_xor_b32_e32 v3, 16, v1
	v_cmp_lt_i32_e32 vcc, v3, v2
	s_waitcnt lgkmcnt(0)
	v_lshl_add_u64 v[66:67], s[4:5], 0, v[64:65]
	v_lshl_add_u64 v[68:69], s[8:9], 0, v[64:65]
	v_cndmask_b32_e32 v3, v1, v3, vcc
	v_lshlrev_b32_e32 v126, 2, v3
	v_xor_b32_e32 v3, 32, v1
	v_cmp_lt_i32_e32 vcc, v3, v2
	v_or_b32_e32 v2, 0x400, v64
	v_lshl_add_u64 v[70:71], s[12:13], 0, v[64:65]
	v_cndmask_b32_e32 v1, v1, v3, vcc
	v_mov_b32_e32 v3, v65
	v_lshl_add_u64 v[74:75], s[8:9], 0, v[2:3]
	v_lshl_add_u64 v[76:77], s[12:13], 0, v[2:3]
	v_lshl_add_u64 v[78:79], s[10:11], 0, v[2:3]
	v_or_b32_e32 v2, 0x800, v64
	v_lshl_add_u64 v[80:81], s[8:9], 0, v[2:3]
	v_lshl_add_u64 v[82:83], s[12:13], 0, v[2:3]
	v_lshl_add_u64 v[84:85], s[10:11], 0, v[2:3]
	v_or_b32_e32 v2, 0xc00, v64
	v_lshl_add_u64 v[86:87], s[8:9], 0, v[2:3]
	v_lshl_add_u64 v[88:89], s[12:13], 0, v[2:3]
	v_lshl_add_u64 v[90:91], s[10:11], 0, v[2:3]
	v_or_b32_e32 v2, 0x1000, v64
	v_lshl_add_u64 v[92:93], s[8:9], 0, v[2:3]
	v_lshl_add_u64 v[94:95], s[12:13], 0, v[2:3]
	v_lshl_add_u64 v[96:97], s[10:11], 0, v[2:3]
	v_or_b32_e32 v2, 0x1400, v64
	v_lshl_add_u64 v[72:73], s[10:11], 0, v[64:65]
	v_lshl_add_u64 v[98:99], s[8:9], 0, v[2:3]
	v_lshl_add_u64 v[100:101], s[12:13], 0, v[2:3]
	v_lshl_add_u64 v[102:103], s[10:11], 0, v[2:3]
	v_or_b32_e32 v2, 0x1800, v64
	v_or_b32_e32 v64, 0x1c00, v64
	v_lshl_add_u64 v[104:105], s[8:9], 0, v[2:3]
	v_lshl_add_u64 v[110:111], s[8:9], 0, v[64:65]
	s_add_i32 s8, s0, s22
	s_ashr_i32 s9, s8, 31
	s_lshl_b64 s[8:9], s[8:9], 12
	v_lshl_add_u64 v[108:109], s[10:11], 0, v[2:3]
	v_lshl_add_u64 v[114:115], s[10:11], 0, v[64:65]
	s_add_u32 s10, s26, s8
	s_addc_u32 s11, s27, s9
	s_ashr_i32 s53, s52, 31
	v_readlane_b32 s9, v255, 6
	v_lshl_add_u64 v[106:107], s[12:13], 0, v[2:3]
	v_lshl_add_u64 v[112:113], s[12:13], 0, v[64:65]
	s_lshl_b64 s[12:13], s[52:53], 12
	s_ashr_i32 s7, s6, 31
	s_ashr_i32 s8, s9, 31
	s_add_u32 s6, s6, s9
	s_addc_u32 s7, s7, s8
	s_lshl_b64 s[8:9], s[6:7], 12
	s_add_u32 s8, s26, s8
	s_addc_u32 s9, s27, s9
	s_add_u32 s14, s8, 0x7200800
	s_addc_u32 s15, s9, 0
	s_lshl_b64 s[6:7], s[6:7], 13
	v_and_b32_e32 v0, 63, v0
	s_add_u32 s4, s4, s6
	v_lshlrev_b32_e32 v127, 2, v1
	v_lshlrev_b32_e32 v64, 3, v0
	v_lshlrev_b32_e32 v0, 4, v0
	v_mov_b32_e32 v1, v65
	s_addc_u32 s5, s5, s7
	v_lshl_add_u64 v[0:1], s[4:5], 0, v[0:1]
	s_mov_b64 s[4:5], 0x1c00
	s_movk_i32 s1, 0x1000
	v_lshl_add_u64 v[116:117], v[0:1], 0, s[4:5]
	s_lshl_b64 s[16:17], s[52:53], 13
	v_mov_b32_e32 v128, 0x358637bd
	s_mov_b32 s4, 0xf800000
	v_mov_b32_e32 v129, 0x260
	flat_load_dwordx4 v[150:153], v[68:69]
	global_load_dwordx4 v[154:157], v[70:71], off
	global_load_dwordx4 v[158:161], v[72:73], off
	global_load_dwordx4 v[162:165], v[76:77], off
	flat_load_dwordx4 v[166:169], v[74:75]
	global_load_dwordx4 v[170:173], v[78:79], off
	global_load_dwordx4 v[174:177], v[82:83], off
	flat_load_dwordx4 v[178:181], v[80:81]
	global_load_dwordx4 v[182:185], v[84:85], off
	global_load_dwordx4 v[186:189], v[88:89], off
	flat_load_dwordx4 v[190:193], v[86:87]
	global_load_dwordx4 v[194:197], v[90:91], off
	global_load_dwordx4 v[198:201], v[94:95], off
	flat_load_dwordx4 v[202:205], v[92:93]
	global_load_dwordx4 v[206:209], v[96:97], off
	global_load_dwordx4 v[210:213], v[100:101], off
	flat_load_dwordx4 v[214:217], v[98:99]
	global_load_dwordx4 v[218:221], v[102:103], off
	global_load_dwordx4 v[222:225], v[106:107], off
	flat_load_dwordx4 v[226:229], v[104:105]
	global_load_dwordx4 v[230:233], v[108:109], off
	global_load_dwordx4 v[234:237], v[112:113], off
	flat_load_dwordx4 v[238:241], v[110:111]
	global_load_dwordx4 v[242:245], v[114:115], off
	s_waitcnt vmcnt(0) lgkmcnt(0)
	s_branch .LBB0_1601

.LBB0_1807:
	s_or_b64 exec, exec, s[2:3]
	s_waitcnt lgkmcnt(0)
	v_mov_b64_e32 v[0:1], s[58:59]
	s_barrier
	flat_load_dwordx2 v[0:1], v[0:1] offset:352
	s_waitcnt vmcnt(0)
	v_readfirstlane_b32 s0, v254
	s_ashr_i32 s2, s0, 6
	v_readlane_b32 s5, v255, 6
	s_add_i32 s4, s2, s5
	s_cmpk_lt_i32 s4, 0x2000
	s_waitcnt lgkmcnt(0)
	v_readfirstlane_b32 s1, v1
	v_readfirstlane_b32 s0, v0
	s_cbranch_scc0 .LBB0_1810
	v_mbcnt_lo_u32_b32 v0, -1, 0
	v_mbcnt_hi_u32_b32 v0, -1, v0
	v_and_b32_e32 v1, 64, v0
	v_add_u32_e32 v1, 64, v1
	v_xor_b32_e32 v2, 1, v0
	v_cmp_lt_i32_e32 vcc, v2, v1
	s_load_dwordx2 s[6:7], s[88:89], 0x168
	s_ashr_i32 s3, s5, 31
	v_cndmask_b32_e32 v2, v0, v2, vcc
	v_lshlrev_b32_e32 v16, 2, v2
	v_xor_b32_e32 v2, 2, v0
	v_cmp_lt_i32_e32 vcc, v2, v1
	v_mov_b32_e32 v22, 0x358637bd
	v_mov_b32_e32 v23, 0x260
	v_cndmask_b32_e32 v2, v0, v2, vcc
	v_lshlrev_b32_e32 v17, 2, v2
	v_xor_b32_e32 v2, 4, v0
	v_cmp_lt_i32_e32 vcc, v2, v1
	s_nop 1
	v_cndmask_b32_e32 v2, v0, v2, vcc
	v_lshlrev_b32_e32 v18, 2, v2
	v_xor_b32_e32 v2, 8, v0
	v_cmp_lt_i32_e32 vcc, v2, v1
	s_nop 1
	v_cndmask_b32_e32 v2, v0, v2, vcc
	v_lshlrev_b32_e32 v19, 2, v2
	v_xor_b32_e32 v2, 16, v0
	v_cmp_lt_i32_e32 vcc, v2, v1
	s_nop 1
	v_cndmask_b32_e32 v2, v0, v2, vcc
	v_lshlrev_b32_e32 v20, 2, v2
	v_xor_b32_e32 v2, 32, v0
	v_cmp_lt_i32_e32 vcc, v2, v1
	v_mov_b32_e32 v1, 0
	v_mov_b32_e32 v3, v1
	v_cndmask_b32_e32 v0, v0, v2, vcc
	v_lshlrev_b32_e32 v21, 2, v0
	v_lshlrev_b32_e32 v0, 4, v254
	v_and_b32_e32 v0, 0x3f0, v0
	v_or_b32_e32 v2, 0x1000, v0
	v_lshl_add_u64 v[6:7], s[0:1], 0, v[2:3]
	v_or_b32_e32 v2, 0x1400, v0
	v_lshl_add_u64 v[4:5], s[0:1], 0, v[0:1]
	v_lshl_add_u64 v[8:9], s[0:1], 0, v[2:3]
	v_or_b32_e32 v2, 0x1800, v0
	v_or_b32_e32 v0, 0x1c00, v0
	v_lshl_add_u64 v[10:11], s[0:1], 0, v[2:3]
	v_lshl_add_u64 v[12:13], s[0:1], 0, v[0:1]
	s_ashr_i32 s1, s2, 31
	s_add_u32 s0, s2, s5
	s_addc_u32 s1, s1, s3
	s_lshl_b64 s[0:1], s[0:1], 13
	v_and_b32_e32 v0, 63, v254
	s_waitcnt lgkmcnt(0)
	s_add_u32 s0, s6, s0
	v_lshlrev_b32_e32 v0, 4, v0
	s_addc_u32 s1, s7, s1
	v_lshl_add_u64 v[0:1], s[0:1], 0, v[0:1]
	s_mov_b64 s[0:1], 0x1c00
	s_ashr_i32 s23, s22, 31
	v_lshl_add_u64 v[14:15], v[0:1], 0, s[0:1]
	s_lshl_b64 s[2:3], s[22:23], 13
	s_mov_b32 s5, 0xf800000
	flat_load_dwordx4 v[150:153], v[4:5]
	flat_load_dwordx4 v[154:157], v[4:5] offset:1024
	flat_load_dwordx4 v[158:161], v[4:5] offset:2048
	flat_load_dwordx4 v[162:165], v[4:5] offset:3072
	flat_load_dwordx4 v[166:169], v[6:7]
	flat_load_dwordx4 v[170:173], v[8:9]
	flat_load_dwordx4 v[174:177], v[10:11]
	flat_load_dwordx4 v[178:181], v[12:13]
	s_waitcnt vmcnt(0) lgkmcnt(0)
